# load segments at s_setprio 1, MMA segments at priority 0 (inverted priorities) in the GEMM K-loops
# speedup vs baseline: 1.0126x; 1.0003x over previous
; template <class Epi, class Sched, bool ALIGN_EPI = false, bool SP2 = false>
; __device__ __forceinline__ void gemm_phase(PG8_LAS unsigned char* lds, const Gemm g, const Sched& S, const Epi& E) {
;     ...
;         const bool has_next = S.next(ui + 1, nxt);
;         const char* nA = has_next ? (const char*)g.A + (size_t)nxt.pm * tstepA : cA; const char* nB = has_next ? (const char*)g.Bt + (size_t)nxt.pn * tstepB : cB;
;     ...
;         if constexpr (Epi::PEEL) {
;             const char* a1 = cA + kstepA; const char* a2 = cA + 2 * kstepA; const char* b2 = cB + 2 * kstepB; const char* a3 = a2 + kstepA; const char* b3 = b2 + kstepB;
;             PG8_ITER(8);
.LBB0_160:
	s_ashr_i32 s55, s54, 31
	s_lshl_b64 s[2:3], s[54:55], 15
	v_readlane_b32 s8, v255, 15
	s_add_u32 s12, s8, s2
	v_readlane_b32 s2, v255, 16
	s_addc_u32 s13, s2, s3
	s_ashr_i32 s49, s48, 31
	s_lshl_b64 s[2:3], s[48:49], 19
	v_readlane_b32 s8, v255, 29
	s_add_u32 s46, s8, s2
	v_readlane_b32 s2, v255, 40
	s_addc_u32 s47, s2, s3
	s_add_u32 s28, s24, 0x800000
	s_addc_u32 s29, s25, 0
	s_add_u32 s42, s24, 0xc00000
	s_addc_u32 s43, s25, 0
	s_add_i32 s55, 0, 0x10000
	s_and_b64 s[2:3], s[30:31], exec
	s_cselect_b32 s27, s13, s25
	s_cselect_b32 s44, s12, s24
	s_add_i32 vcc_hi, 0, 0x14000
	v_add_u32_e32 v142, s55, v97
	v_add_u32_e32 v143, vcc_hi, v97
	ds_read_b128 v[0:3], v142
	ds_read_b128 v[4:7], v142 offset:1024
	ds_read_b128 v[8:11], v142 offset:2048
	ds_read_b128 v[12:15], v142 offset:3072
	ds_read_b128 v[16:19], v143
	s_waitcnt lgkmcnt(0)
	ds_read_b128 v[20:23], v143 offset:1024
	ds_read_b128 v[24:27], v143 offset:2048
	ds_read_b128 v[28:31], v143 offset:3072
	v_writelane_b32 v255, s30, 33
	s_and_b64 s[2:3], s[30:31], exec
	s_cselect_b32 s45, s47, s1
	v_writelane_b32 v255, s31, 34
	s_cselect_b32 s49, s46, s0
	s_add_u32 s2, s24, 0x404000
	s_addc_u32 s3, s25, 0
	s_add_i32 s50, s22, 0xc000
	s_mov_b32 m0, s50
	s_add_i32 s51, s22, 0xe000
	ds_read_b128 v[32:35], v161
	ds_read_b128 v[36:39], v161 offset:1024
	ds_read_b128 v[40:43], v161 offset:2048
	ds_read_b128 v[44:47], v161 offset:3072
	ds_read_b128 v[48:51], v161 offset:4096
	ds_read_b128 v[52:55], v161 offset:5120
	ds_read_b128 v[56:59], v161 offset:6144
	ds_read_b128 v[60:63], v161 offset:7168
	global_load_lds_dwordx4 v130, s[2:3]
	s_mov_b32 m0, s51
	s_nop 0
	global_load_lds_dwordx4 v134, s[2:3]
	s_setprio 0
	s_waitcnt vmcnt(8)
	s_waitcnt lgkmcnt(0)
	s_barrier
	s_waitcnt lgkmcnt(0)
	v_mfma_f32_16x16x32_bf16 v[64:67], v[0:3], v[32:35], 0
	v_mfma_f32_16x16x32_bf16 v[68:71], v[8:11], v[32:35], 0
	v_mfma_f32_16x16x32_bf16 v[72:75], v[0:3], v[40:43], 0
	v_mfma_f32_16x16x32_bf16 v[76:79], v[8:11], v[40:43], 0
	v_mfma_f32_16x16x32_bf16 v[80:83], v[0:3], v[48:51], 0
	v_mfma_f32_16x16x32_bf16 v[84:87], v[8:11], v[48:51], 0
	v_mfma_f32_16x16x32_bf16 v[88:91], v[0:3], v[56:59], 0
	v_mfma_f32_16x16x32_bf16 v[92:95], v[8:11], v[56:59], 0
	v_mfma_f32_16x16x32_bf16 v[64:67], v[4:7], v[36:39], v[64:67]
	v_mfma_f32_16x16x32_bf16 v[68:71], v[12:15], v[36:39], v[68:71]
	v_mfma_f32_16x16x32_bf16 v[72:75], v[4:7], v[44:47], v[72:75]
	v_mfma_f32_16x16x32_bf16 v[76:79], v[12:15], v[44:47], v[76:79]
	v_mfma_f32_16x16x32_bf16 v[80:83], v[4:7], v[52:55], v[80:83]
	v_mfma_f32_16x16x32_bf16 v[84:87], v[12:15], v[52:55], v[84:87]
	v_mfma_f32_16x16x32_bf16 v[88:91], v[4:7], v[60:63], v[88:91]
	v_mfma_f32_16x16x32_bf16 v[98:101], v[12:15], v[60:63], v[92:95]
	v_mfma_f32_16x16x32_bf16 v[92:95], v[16:19], v[32:35], 0
	v_mfma_f32_16x16x32_bf16 v[32:35], v[24:27], v[32:35], 0
	v_mfma_f32_16x16x32_bf16 v[106:109], v[20:23], v[36:39], v[92:95]
	v_mfma_f32_16x16x32_bf16 v[32:35], v[28:31], v[36:39], v[32:35]
	v_mfma_f32_16x16x32_bf16 v[36:39], v[16:19], v[40:43], 0
	v_mfma_f32_16x16x32_bf16 v[40:43], v[24:27], v[40:43], 0
	v_mfma_f32_16x16x32_bf16 v[36:39], v[20:23], v[44:47], v[36:39]
	v_mfma_f32_16x16x32_bf16 v[40:43], v[28:31], v[44:47], v[40:43]
	v_mfma_f32_16x16x32_bf16 v[44:47], v[16:19], v[48:51], 0
	v_mfma_f32_16x16x32_bf16 v[48:51], v[24:27], v[48:51], 0
	v_mfma_f32_16x16x32_bf16 v[44:47], v[20:23], v[52:55], v[44:47]
	v_mfma_f32_16x16x32_bf16 v[48:51], v[28:31], v[52:55], v[48:51]
	v_mfma_f32_16x16x32_bf16 v[52:55], v[16:19], v[56:59], 0
	v_mfma_f32_16x16x32_bf16 v[56:59], v[24:27], v[56:59], 0
	v_mfma_f32_16x16x32_bf16 v[52:55], v[20:23], v[60:63], v[52:55]
	v_mfma_f32_16x16x32_bf16 v[56:59], v[28:31], v[60:63], v[56:59]
	s_barrier
	s_setprio 1
	v_lshl_add_u64 v[158:159], s[0:1], 0, v[132:133]
	s_mov_b64 s[2:3], 0x100
	s_add_i32 s55, s55, s10
	v_lshl_add_u64 v[144:145], v[158:159], 0, s[2:3]
	s_mov_b32 m0, s55
	v_lshl_add_u64 v[178:179], s[0:1], 0, v[136:137]
	s_add_i32 vcc_lo, s55, 0x2000
	ds_read_b128 v[60:63], v161 offset:16384
	ds_read_b128 v[92:95], v161 offset:17408
	ds_read_b128 v[102:105], v161 offset:18432
	ds_read_b128 v[110:113], v161 offset:19456
	ds_read_b128 v[114:117], v161 offset:20480
	ds_read_b128 v[118:121], v161 offset:21504
	ds_read_b128 v[122:125], v161 offset:22528
	ds_read_b128 v[126:129], v161 offset:23552
	global_load_lds_dwordx4 v[144:145], off
	v_lshl_add_u64 v[144:145], v[178:179], 0, s[2:3]
	s_add_u32 s2, s0, 0x40100
	s_mov_b32 m0, vcc_lo
	s_addc_u32 s3, s1, 0
	s_add_i32 vcc_hi, vcc_hi, s10
	global_load_lds_dwordx4 v[144:145], off
	s_mov_b32 m0, vcc_hi
	s_add_i32 s56, vcc_hi, 0x2000
	global_load_lds_dwordx4 v132, s[2:3]
	s_mov_b32 m0, s56
	s_nop 0
	global_load_lds_dwordx4 v136, s[2:3]
	s_mov_b32 m0, s22
	s_nop 0
	global_load_lds_dwordx4 v130, s[28:29]
	s_mov_b32 m0, s23
	s_nop 0
	global_load_lds_dwordx4 v134, s[28:29]
	s_setprio 0
	s_waitcnt vmcnt(8)
	s_waitcnt lgkmcnt(0)
	s_barrier
	s_waitcnt lgkmcnt(0)
	v_mfma_f32_16x16x32_bf16 v[144:147], v[0:3], v[60:63], 0
	v_mfma_f32_16x16x32_bf16 v[154:157], v[0:3], v[102:105], 0
	v_mfma_f32_16x16x32_bf16 v[166:169], v[0:3], v[114:117], 0
	v_mfma_f32_16x16x32_bf16 v[0:3], v[0:3], v[122:125], 0
	v_mfma_f32_16x16x32_bf16 v[146:149], v[4:7], v[92:95], v[144:147]
	v_mfma_f32_16x16x32_bf16 v[154:157], v[4:7], v[110:113], v[154:157]
	v_mfma_f32_16x16x32_bf16 v[166:169], v[4:7], v[118:121], v[166:169]
	v_mfma_f32_16x16x32_bf16 v[0:3], v[4:7], v[126:129], v[0:3]
	v_mfma_f32_16x16x32_bf16 v[4:7], v[8:11], v[122:125], 0
	v_mfma_f32_16x16x32_bf16 v[150:153], v[8:11], v[60:63], 0
	v_mfma_f32_16x16x32_bf16 v[162:165], v[8:11], v[102:105], 0
	v_mfma_f32_16x16x32_bf16 v[170:173], v[8:11], v[114:117], 0
	v_mfma_f32_16x16x32_bf16 v[4:7], v[12:15], v[126:129], v[4:7]
	v_mfma_f32_16x16x32_bf16 v[150:153], v[12:15], v[92:95], v[150:153]
	v_mfma_f32_16x16x32_bf16 v[162:165], v[12:15], v[110:113], v[162:165]
	v_mfma_f32_16x16x32_bf16 v[170:173], v[12:15], v[118:121], v[170:173]
	v_mfma_f32_16x16x32_bf16 v[12:15], v[24:27], v[60:63], 0
	v_mfma_f32_16x16x32_bf16 v[174:177], v[28:31], v[92:95], v[12:15]
	v_mfma_f32_16x16x32_bf16 v[12:15], v[16:19], v[102:105], 0
	v_mfma_f32_16x16x32_bf16 v[180:183], v[20:23], v[110:113], v[12:15]
	v_mfma_f32_16x16x32_bf16 v[12:15], v[24:27], v[102:105], 0
	v_mfma_f32_16x16x32_bf16 v[184:187], v[28:31], v[110:113], v[12:15]
	v_mfma_f32_16x16x32_bf16 v[12:15], v[16:19], v[114:117], 0
	v_mfma_f32_16x16x32_bf16 v[188:191], v[20:23], v[118:121], v[12:15]
	v_mfma_f32_16x16x32_bf16 v[12:15], v[24:27], v[114:117], 0
	v_mfma_f32_16x16x32_bf16 v[8:11], v[16:19], v[60:63], 0
	v_mfma_f32_16x16x32_bf16 v[192:195], v[28:31], v[118:121], v[12:15]
	v_mfma_f32_16x16x32_bf16 v[12:15], v[16:19], v[122:125], 0
	v_mfma_f32_16x16x32_bf16 v[8:11], v[20:23], v[92:95], v[8:11]
	v_mfma_f32_16x16x32_bf16 v[196:199], v[20:23], v[126:129], v[12:15]
	v_mfma_f32_16x16x32_bf16 v[12:15], v[24:27], v[122:125], 0
	v_mfma_f32_16x16x32_bf16 v[200:203], v[28:31], v[126:129], v[12:15]
	s_barrier
	s_setprio 1
	s_add_i32 s30, 0, 0x18000
	s_add_i32 s57, 0, 0x1c000
	v_add_u32_e32 v144, s30, v97
	v_add_u32_e32 v145, s57, v97
	s_nop 0
	ds_read_b128 v[12:15], v144
	ds_read_b128 v[16:19], v144 offset:1024
	ds_read_b128 v[24:27], v144 offset:2048
	ds_read_b128 v[204:207], v144 offset:3072
	ds_read_b128 v[208:211], v145
	ds_read_b128 v[212:215], v145 offset:1024
	ds_read_b128 v[216:219], v145 offset:2048
	ds_read_b128 v[220:223], v145 offset:3072
	s_add_u32 s2, s24, 0x804000
	s_addc_u32 s3, s25, 0
	s_mov_b32 m0, s39
	ds_read_b128 v[20:23], v161 offset:32768
	ds_read_b128 v[28:31], v161 offset:33792
	ds_read_b128 v[60:63], v161 offset:34816
	ds_read_b128 v[224:227], v161 offset:35840
	ds_read_b128 v[228:231], v161 offset:36864
	ds_read_b128 v[234:237], v161 offset:37888
	ds_read_b128 v[238:241], v161 offset:38912
	ds_read_b128 v[242:245], v161 offset:39936
	global_load_lds_dwordx4 v130, s[2:3]
	s_mov_b32 m0, s52
	s_nop 0
	global_load_lds_dwordx4 v134, s[2:3]
	s_setprio 0
	s_waitcnt vmcnt(8)
	s_waitcnt lgkmcnt(0)
	s_barrier
	s_waitcnt lgkmcnt(0)
	v_mfma_f32_16x16x32_bf16 v[64:67], v[12:15], v[20:23], v[64:67]
	v_mfma_f32_16x16x32_bf16 v[126:129], v[16:19], v[28:31], v[64:67]
	v_mfma_f32_16x16x32_bf16 v[64:67], v[24:27], v[20:23], v[68:71]
	v_mfma_f32_16x16x32_bf16 v[118:121], v[204:207], v[28:31], v[64:67]
	v_mfma_f32_16x16x32_bf16 v[64:67], v[12:15], v[60:63], v[72:75]
	v_mfma_f32_16x16x32_bf16 v[110:113], v[16:19], v[224:227], v[64:67]
	v_mfma_f32_16x16x32_bf16 v[64:67], v[24:27], v[60:63], v[76:79]
	v_mfma_f32_16x16x32_bf16 v[102:105], v[204:207], v[224:227], v[64:67]
	v_mfma_f32_16x16x32_bf16 v[64:67], v[12:15], v[228:231], v[80:83]
	v_mfma_f32_16x16x32_bf16 v[92:95], v[16:19], v[234:237], v[64:67]
	v_mfma_f32_16x16x32_bf16 v[64:67], v[24:27], v[228:231], v[84:87]
	v_mfma_f32_16x16x32_bf16 v[84:87], v[204:207], v[234:237], v[64:67]
	v_mfma_f32_16x16x32_bf16 v[64:67], v[12:15], v[238:241], v[88:91]
	v_mfma_f32_16x16x32_bf16 v[76:79], v[16:19], v[242:245], v[64:67]
	v_mfma_f32_16x16x32_bf16 v[64:67], v[24:27], v[238:241], v[98:101]
	v_mfma_f32_16x16x32_bf16 v[68:71], v[204:207], v[242:245], v[64:67]
	v_mfma_f32_16x16x32_bf16 v[64:67], v[208:211], v[20:23], v[106:109]
	v_mfma_f32_16x16x32_bf16 v[20:23], v[216:219], v[20:23], v[32:35]
	v_mfma_f32_16x16x32_bf16 v[114:117], v[220:223], v[28:31], v[20:23]
	v_mfma_f32_16x16x32_bf16 v[20:23], v[208:211], v[60:63], v[36:39]
	v_mfma_f32_16x16x32_bf16 v[106:109], v[212:215], v[224:227], v[20:23]
	v_mfma_f32_16x16x32_bf16 v[20:23], v[216:219], v[60:63], v[40:43]
	v_mfma_f32_16x16x32_bf16 v[98:101], v[220:223], v[224:227], v[20:23]
	v_mfma_f32_16x16x32_bf16 v[20:23], v[208:211], v[228:231], v[44:47]
	v_mfma_f32_16x16x32_bf16 v[88:91], v[212:215], v[234:237], v[20:23]
	v_mfma_f32_16x16x32_bf16 v[20:23], v[216:219], v[228:231], v[48:51]
	v_mfma_f32_16x16x32_bf16 v[80:83], v[220:223], v[234:237], v[20:23]
	v_mfma_f32_16x16x32_bf16 v[20:23], v[208:211], v[238:241], v[52:55]
	v_mfma_f32_16x16x32_bf16 v[72:75], v[212:215], v[242:245], v[20:23]
	v_mfma_f32_16x16x32_bf16 v[20:23], v[216:219], v[238:241], v[56:59]
	v_mfma_f32_16x16x32_bf16 v[122:125], v[212:215], v[28:31], v[64:67]
	v_mfma_f32_16x16x32_bf16 v[64:67], v[220:223], v[242:245], v[20:23]
	s_barrier
; template <class Epi, class Sched, bool ALIGN_EPI = false, bool SP2 = false>
; __device__ __forceinline__ void gemm_phase(PG8_LAS unsigned char* lds, const Gemm g, const Sched& S, const Epi& E) {
;     ...
;             const bool last = (t == nt - 2);
;             const char* a1 = cA + (size_t)(t + 1) * kstepA;
;             const char* a2 = last ? nA : cA + (size_t)(t + 2) * kstepA; const char* b2 = last ? nB : cB + (size_t)(t + 2) * kstepB;
	s_setprio 1
	s_mov_b64 s[2:3], 0x180
	s_add_i32 s30, s30, s10
	s_nop 1
	v_lshl_add_u64 v[20:21], v[158:159], 0, s[2:3]
	s_mov_b32 m0, s30
	s_add_i32 s31, s30, 0x2000
	ds_read_b128 v[32:35], v161 offset:49152
	ds_read_b128 v[40:43], v161 offset:50176
	ds_read_b128 v[224:227], v161 offset:51200
	ds_read_b128 v[228:231], v161 offset:52224
	ds_read_b128 v[234:237], v161 offset:53248
	ds_read_b128 v[238:241], v161 offset:54272
	ds_read_b128 v[242:245], v161 offset:55296
	ds_read_b128 v[246:249], v161 offset:56320
	global_load_lds_dwordx4 v[20:21], off
	v_lshl_add_u64 v[20:21], v[178:179], 0, s[2:3]
	s_add_u32 s2, s0, 0x40180
	s_mov_b32 m0, s31
	s_addc_u32 s3, s1, 0
	s_add_i32 s57, s57, s10
	global_load_lds_dwordx4 v[20:21], off
	s_mov_b32 m0, s57
	s_add_i32 s96, s57, 0x2000
	global_load_lds_dwordx4 v132, s[2:3]
	s_mov_b32 m0, s96
	s_nop 0
	global_load_lds_dwordx4 v136, s[2:3]
	s_mov_b32 m0, s11
	s_nop 0
	global_load_lds_dwordx4 v130, s[42:43]
	s_mov_b32 m0, s19
	s_nop 0
	global_load_lds_dwordx4 v134, s[42:43]
	s_setprio 0
	s_waitcnt vmcnt(8)
	s_waitcnt lgkmcnt(0)
	s_barrier
	s_waitcnt lgkmcnt(0)
	v_mfma_f32_16x16x32_bf16 v[20:23], v[12:15], v[32:35], v[146:149]
	v_mfma_f32_16x16x32_bf16 v[60:63], v[16:19], v[40:43], v[20:23]
	v_mfma_f32_16x16x32_bf16 v[20:23], v[24:27], v[32:35], v[150:153]
	v_mfma_f32_16x16x32_bf16 v[52:55], v[204:207], v[40:43], v[20:23]
	v_mfma_f32_16x16x32_bf16 v[20:23], v[12:15], v[224:227], v[154:157]
	v_mfma_f32_16x16x32_bf16 v[44:47], v[16:19], v[228:231], v[20:23]
	v_mfma_f32_16x16x32_bf16 v[20:23], v[24:27], v[224:227], v[162:165]
	v_mfma_f32_16x16x32_bf16 v[36:39], v[204:207], v[228:231], v[20:23]
	v_mfma_f32_16x16x32_bf16 v[20:23], v[12:15], v[234:237], v[166:169]
	v_mfma_f32_16x16x32_bf16 v[0:3], v[12:15], v[242:245], v[0:3]
	v_mfma_f32_16x16x32_bf16 v[28:31], v[16:19], v[238:241], v[20:23]
	v_mfma_f32_16x16x32_bf16 v[20:23], v[24:27], v[234:237], v[170:173]
	v_mfma_f32_16x16x32_bf16 v[12:15], v[16:19], v[246:249], v[0:3]
	v_mfma_f32_16x16x32_bf16 v[0:3], v[24:27], v[242:245], v[4:7]
	v_mfma_f32_16x16x32_bf16 v[20:23], v[204:207], v[238:241], v[20:23]
	v_mfma_f32_16x16x32_bf16 v[4:7], v[204:207], v[246:249], v[0:3]
	v_mfma_f32_16x16x32_bf16 v[0:3], v[208:211], v[32:35], v[8:11]
	v_mfma_f32_16x16x32_bf16 v[56:59], v[212:215], v[40:43], v[0:3]
	v_mfma_f32_16x16x32_bf16 v[0:3], v[216:219], v[32:35], v[174:177]
	v_mfma_f32_16x16x32_bf16 v[48:51], v[220:223], v[40:43], v[0:3]
	v_mfma_f32_16x16x32_bf16 v[0:3], v[208:211], v[224:227], v[180:183]
	v_mfma_f32_16x16x32_bf16 v[40:43], v[212:215], v[228:231], v[0:3]
	v_mfma_f32_16x16x32_bf16 v[0:3], v[216:219], v[224:227], v[184:187]
	v_mfma_f32_16x16x32_bf16 v[32:35], v[220:223], v[228:231], v[0:3]
	v_mfma_f32_16x16x32_bf16 v[0:3], v[208:211], v[234:237], v[188:191]
	v_mfma_f32_16x16x32_bf16 v[24:27], v[212:215], v[238:241], v[0:3]
	v_mfma_f32_16x16x32_bf16 v[0:3], v[216:219], v[234:237], v[192:195]
	v_mfma_f32_16x16x32_bf16 v[16:19], v[220:223], v[238:241], v[0:3]
	v_mfma_f32_16x16x32_bf16 v[0:3], v[208:211], v[242:245], v[196:199]
	v_mfma_f32_16x16x32_bf16 v[8:11], v[212:215], v[246:249], v[0:3]
	v_mfma_f32_16x16x32_bf16 v[0:3], v[216:219], v[242:245], v[200:203]
	v_mfma_f32_16x16x32_bf16 v[0:3], v[220:223], v[246:249], v[0:3]
	s_barrier
	s_setprio 1
	s_add_u32 s3, s0, 0x200
	s_addc_u32 s2, s1, 0
	s_add_u32 s0, s24, 0xc04000
	s_addc_u32 s1, s25, 0
	s_mov_b32 s18, 0
.LBB0_161:
	ds_read_b128 v[146:149], v142
	ds_read_b128 v[150:153], v142 offset:1024
	ds_read_b128 v[154:157], v142 offset:2048
	ds_read_b128 v[162:165], v142 offset:3072
	ds_read_b128 v[166:169], v143
	ds_read_b128 v[170:173], v143 offset:1024
	ds_read_b128 v[174:177], v143 offset:2048
	ds_read_b128 v[180:183], v143 offset:3072
	s_add_u32 s8, s0, 0x3fc000
	s_addc_u32 s9, s1, 0
	s_cmp_eq_u32 s18, 12
	s_cselect_b32 s28, s44, s8
	s_cselect_b32 s29, s27, s9
	s_cselect_b32 s42, s49, s3
	s_cselect_b32 s43, s45, s2
	s_add_u32 s24, s28, 0x400000
	s_addc_u32 s25, s29, 0
	s_mov_b32 m0, s50
	ds_read_b128 v[184:187], v161
	ds_read_b128 v[188:191], v161 offset:1024
	ds_read_b128 v[192:195], v161 offset:2048
	ds_read_b128 v[196:199], v161 offset:3072
	ds_read_b128 v[200:203], v161 offset:4096
	ds_read_b128 v[204:207], v161 offset:5120
	ds_read_b128 v[208:211], v161 offset:6144
	ds_read_b128 v[212:215], v161 offset:7168
	global_load_lds_dwordx4 v140, s[0:1]
	s_mov_b32 m0, s51
	s_nop 0
	global_load_lds_dwordx4 v138, s[0:1]
	s_setprio 0
	s_waitcnt vmcnt(8)
	s_waitcnt lgkmcnt(0)
	s_barrier
	s_waitcnt lgkmcnt(0)
	v_mfma_f32_16x16x32_bf16 v[126:129], v[146:149], v[184:187], v[126:129]
	v_mfma_f32_16x16x32_bf16 v[118:121], v[154:157], v[184:187], v[118:121]
	v_mfma_f32_16x16x32_bf16 v[102:105], v[154:157], v[192:195], v[102:105]
	v_mfma_f32_16x16x32_bf16 v[110:113], v[146:149], v[192:195], v[110:113]
	v_mfma_f32_16x16x32_bf16 v[92:95], v[146:149], v[200:203], v[92:95]
	v_mfma_f32_16x16x32_bf16 v[84:87], v[154:157], v[200:203], v[84:87]
	v_mfma_f32_16x16x32_bf16 v[68:71], v[154:157], v[208:211], v[68:71]
	v_mfma_f32_16x16x32_bf16 v[76:79], v[146:149], v[208:211], v[76:79]
	v_mfma_f32_16x16x32_bf16 v[126:129], v[150:153], v[188:191], v[126:129]
	v_mfma_f32_16x16x32_bf16 v[118:121], v[162:165], v[188:191], v[118:121]
	v_mfma_f32_16x16x32_bf16 v[102:105], v[162:165], v[196:199], v[102:105]
	v_mfma_f32_16x16x32_bf16 v[110:113], v[150:153], v[196:199], v[110:113]
	v_mfma_f32_16x16x32_bf16 v[92:95], v[150:153], v[204:207], v[92:95]
	v_mfma_f32_16x16x32_bf16 v[84:87], v[162:165], v[204:207], v[84:87]
	v_mfma_f32_16x16x32_bf16 v[68:71], v[162:165], v[212:215], v[68:71]
	v_mfma_f32_16x16x32_bf16 v[76:79], v[150:153], v[212:215], v[76:79]
	v_mfma_f32_16x16x32_bf16 v[122:125], v[166:169], v[184:187], v[122:125]
	v_mfma_f32_16x16x32_bf16 v[114:117], v[174:177], v[184:187], v[114:117]
	v_mfma_f32_16x16x32_bf16 v[98:101], v[174:177], v[192:195], v[98:101]
	v_mfma_f32_16x16x32_bf16 v[106:109], v[166:169], v[192:195], v[106:109]
	v_mfma_f32_16x16x32_bf16 v[88:91], v[166:169], v[200:203], v[88:91]
	v_mfma_f32_16x16x32_bf16 v[80:83], v[174:177], v[200:203], v[80:83]
	v_mfma_f32_16x16x32_bf16 v[64:67], v[174:177], v[208:211], v[64:67]
	v_mfma_f32_16x16x32_bf16 v[72:75], v[166:169], v[208:211], v[72:75]
	v_mfma_f32_16x16x32_bf16 v[122:125], v[170:173], v[188:191], v[122:125]
	v_mfma_f32_16x16x32_bf16 v[114:117], v[180:183], v[188:191], v[114:117]
	v_mfma_f32_16x16x32_bf16 v[98:101], v[180:183], v[196:199], v[98:101]
	v_mfma_f32_16x16x32_bf16 v[106:109], v[170:173], v[196:199], v[106:109]
	v_mfma_f32_16x16x32_bf16 v[88:91], v[170:173], v[204:207], v[88:91]
	v_mfma_f32_16x16x32_bf16 v[80:83], v[180:183], v[204:207], v[80:83]
	v_mfma_f32_16x16x32_bf16 v[64:67], v[180:183], v[212:215], v[64:67]
	v_mfma_f32_16x16x32_bf16 v[72:75], v[170:173], v[212:215], v[72:75]
	s_barrier
	s_setprio 1
	s_mov_b32 m0, s55
	s_add_u32 s8, s42, 0x40000
	ds_read_b128 v[184:187], v161 offset:16384
	ds_read_b128 v[188:191], v161 offset:17408
	ds_read_b128 v[192:195], v161 offset:18432
	ds_read_b128 v[196:199], v161 offset:19456
	ds_read_b128 v[200:203], v161 offset:20480
	ds_read_b128 v[204:207], v161 offset:21504
	ds_read_b128 v[208:211], v161 offset:22528
	ds_read_b128 v[212:215], v161 offset:23552
	global_load_lds_dwordx4 v132, s[42:43]
	s_mov_b32 m0, vcc_lo
	s_addc_u32 s9, s43, 0
	global_load_lds_dwordx4 v136, s[42:43]
	s_mov_b32 m0, vcc_hi
	s_nop 0
	global_load_lds_dwordx4 v132, s[8:9]
	s_mov_b32 m0, s56
	s_nop 0
	global_load_lds_dwordx4 v136, s[8:9]
	s_mov_b32 m0, s22
	s_nop 0
	global_load_lds_dwordx4 v130, s[28:29]
	s_mov_b32 m0, s23
	s_nop 0
	global_load_lds_dwordx4 v134, s[28:29]
	s_setprio 0
	s_waitcnt vmcnt(8)
	s_waitcnt lgkmcnt(0)
	s_barrier
	s_waitcnt lgkmcnt(0)
	v_mfma_f32_16x16x32_bf16 v[60:63], v[146:149], v[184:187], v[60:63]
	v_mfma_f32_16x16x32_bf16 v[52:55], v[154:157], v[184:187], v[52:55]
	v_mfma_f32_16x16x32_bf16 v[36:39], v[154:157], v[192:195], v[36:39]
	v_mfma_f32_16x16x32_bf16 v[44:47], v[146:149], v[192:195], v[44:47]
	v_mfma_f32_16x16x32_bf16 v[28:31], v[146:149], v[200:203], v[28:31]
	v_mfma_f32_16x16x32_bf16 v[20:23], v[154:157], v[200:203], v[20:23]
	v_mfma_f32_16x16x32_bf16 v[4:7], v[154:157], v[208:211], v[4:7]
	v_mfma_f32_16x16x32_bf16 v[12:15], v[146:149], v[208:211], v[12:15]
	v_mfma_f32_16x16x32_bf16 v[60:63], v[150:153], v[188:191], v[60:63]
	v_mfma_f32_16x16x32_bf16 v[52:55], v[162:165], v[188:191], v[52:55]
	v_mfma_f32_16x16x32_bf16 v[36:39], v[162:165], v[196:199], v[36:39]
	v_mfma_f32_16x16x32_bf16 v[44:47], v[150:153], v[196:199], v[44:47]
	v_mfma_f32_16x16x32_bf16 v[28:31], v[150:153], v[204:207], v[28:31]
	v_mfma_f32_16x16x32_bf16 v[20:23], v[162:165], v[204:207], v[20:23]
	v_mfma_f32_16x16x32_bf16 v[4:7], v[162:165], v[212:215], v[4:7]
	v_mfma_f32_16x16x32_bf16 v[12:15], v[150:153], v[212:215], v[12:15]
	v_mfma_f32_16x16x32_bf16 v[56:59], v[166:169], v[184:187], v[56:59]
	v_mfma_f32_16x16x32_bf16 v[48:51], v[174:177], v[184:187], v[48:51]
	v_mfma_f32_16x16x32_bf16 v[32:35], v[174:177], v[192:195], v[32:35]
	v_mfma_f32_16x16x32_bf16 v[40:43], v[166:169], v[192:195], v[40:43]
	v_mfma_f32_16x16x32_bf16 v[24:27], v[166:169], v[200:203], v[24:27]
	v_mfma_f32_16x16x32_bf16 v[16:19], v[174:177], v[200:203], v[16:19]
	v_mfma_f32_16x16x32_bf16 v[0:3], v[174:177], v[208:211], v[0:3]
	v_mfma_f32_16x16x32_bf16 v[8:11], v[166:169], v[208:211], v[8:11]
	v_mfma_f32_16x16x32_bf16 v[56:59], v[170:173], v[188:191], v[56:59]
	v_mfma_f32_16x16x32_bf16 v[48:51], v[180:183], v[188:191], v[48:51]
	v_mfma_f32_16x16x32_bf16 v[32:35], v[180:183], v[196:199], v[32:35]
	v_mfma_f32_16x16x32_bf16 v[40:43], v[170:173], v[196:199], v[40:43]
	v_mfma_f32_16x16x32_bf16 v[24:27], v[170:173], v[204:207], v[24:27]
	v_mfma_f32_16x16x32_bf16 v[16:19], v[180:183], v[204:207], v[16:19]
	v_mfma_f32_16x16x32_bf16 v[0:3], v[180:183], v[212:215], v[0:3]
	v_mfma_f32_16x16x32_bf16 v[8:11], v[170:173], v[212:215], v[8:11]
	s_barrier
	s_setprio 1
	ds_read_b128 v[146:149], v144
	ds_read_b128 v[150:153], v144 offset:1024
	ds_read_b128 v[154:157], v144 offset:2048
	ds_read_b128 v[162:165], v144 offset:3072
	ds_read_b128 v[166:169], v145
	ds_read_b128 v[170:173], v145 offset:1024
	ds_read_b128 v[174:177], v145 offset:2048
	ds_read_b128 v[180:183], v145 offset:3072
	s_add_u32 s8, s28, 0x4000
	s_addc_u32 s9, s29, 0
	s_mov_b32 m0, s39
	ds_read_b128 v[184:187], v161 offset:32768
	ds_read_b128 v[188:191], v161 offset:33792
	ds_read_b128 v[192:195], v161 offset:34816
	ds_read_b128 v[196:199], v161 offset:35840
	ds_read_b128 v[200:203], v161 offset:36864
	ds_read_b128 v[204:207], v161 offset:37888
	ds_read_b128 v[208:211], v161 offset:38912
	ds_read_b128 v[212:215], v161 offset:39936
	global_load_lds_dwordx4 v130, s[8:9]
	s_mov_b32 m0, s52
	s_nop 0
	global_load_lds_dwordx4 v134, s[8:9]
	s_setprio 0
	s_waitcnt vmcnt(8)
	s_waitcnt lgkmcnt(0)
	s_barrier
; #define PG8_BAR __builtin_amdgcn_s_barrier()
; template <class Epi, class Sched, bool ALIGN_EPI = false, bool SP2 = false>
; __device__ __forceinline__ void gemm_phase(PG8_LAS unsigned char* lds, const Gemm g, const Sched& S, const Epi& E) {
;     ...
;         for (int t = (Epi::PEEL ? 2 : 0); t < nt; t += 2) {
;             const bool last = (t == nt - 2);
;             const char* a1 = cA + (size_t)(t + 1) * kstepA;
;             const char* a2 = last ? nA : cA + (size_t)(t + 2) * kstepA; const char* b2 = last ? nB : cB + (size_t)(t + 2) * kstepB;
;             const char* a3 = a2 + kstepA; const char* b3 = b2 + kstepB;
;             PG8_ITER(8);
;         }
;     ...
;         if constexpr (ALIGN_EPI) { if (wr == 0) PG8_BAR; }
	s_waitcnt lgkmcnt(0)
	v_mfma_f32_16x16x32_bf16 v[126:129], v[146:149], v[184:187], v[126:129]
	v_mfma_f32_16x16x32_bf16 v[118:121], v[154:157], v[184:187], v[118:121]
	v_mfma_f32_16x16x32_bf16 v[102:105], v[154:157], v[192:195], v[102:105]
	v_mfma_f32_16x16x32_bf16 v[110:113], v[146:149], v[192:195], v[110:113]
	v_mfma_f32_16x16x32_bf16 v[92:95], v[146:149], v[200:203], v[92:95]
	v_mfma_f32_16x16x32_bf16 v[84:87], v[154:157], v[200:203], v[84:87]
	v_mfma_f32_16x16x32_bf16 v[68:71], v[154:157], v[208:211], v[68:71]
	v_mfma_f32_16x16x32_bf16 v[76:79], v[146:149], v[208:211], v[76:79]
	v_mfma_f32_16x16x32_bf16 v[126:129], v[150:153], v[188:191], v[126:129]
	v_mfma_f32_16x16x32_bf16 v[118:121], v[162:165], v[188:191], v[118:121]
	v_mfma_f32_16x16x32_bf16 v[102:105], v[162:165], v[196:199], v[102:105]
	v_mfma_f32_16x16x32_bf16 v[110:113], v[150:153], v[196:199], v[110:113]
	v_mfma_f32_16x16x32_bf16 v[92:95], v[150:153], v[204:207], v[92:95]
	v_mfma_f32_16x16x32_bf16 v[84:87], v[162:165], v[204:207], v[84:87]
	v_mfma_f32_16x16x32_bf16 v[68:71], v[162:165], v[212:215], v[68:71]
	v_mfma_f32_16x16x32_bf16 v[76:79], v[150:153], v[212:215], v[76:79]
	v_mfma_f32_16x16x32_bf16 v[122:125], v[166:169], v[184:187], v[122:125]
	v_mfma_f32_16x16x32_bf16 v[114:117], v[174:177], v[184:187], v[114:117]
	v_mfma_f32_16x16x32_bf16 v[98:101], v[174:177], v[192:195], v[98:101]
	v_mfma_f32_16x16x32_bf16 v[106:109], v[166:169], v[192:195], v[106:109]
	v_mfma_f32_16x16x32_bf16 v[88:91], v[166:169], v[200:203], v[88:91]
	v_mfma_f32_16x16x32_bf16 v[80:83], v[174:177], v[200:203], v[80:83]
	v_mfma_f32_16x16x32_bf16 v[64:67], v[174:177], v[208:211], v[64:67]
	v_mfma_f32_16x16x32_bf16 v[72:75], v[166:169], v[208:211], v[72:75]
	v_mfma_f32_16x16x32_bf16 v[122:125], v[170:173], v[188:191], v[122:125]
	v_mfma_f32_16x16x32_bf16 v[114:117], v[180:183], v[188:191], v[114:117]
	v_mfma_f32_16x16x32_bf16 v[98:101], v[180:183], v[196:199], v[98:101]
	v_mfma_f32_16x16x32_bf16 v[106:109], v[170:173], v[196:199], v[106:109]
	v_mfma_f32_16x16x32_bf16 v[88:91], v[170:173], v[204:207], v[88:91]
	v_mfma_f32_16x16x32_bf16 v[80:83], v[180:183], v[204:207], v[80:83]
	v_mfma_f32_16x16x32_bf16 v[64:67], v[180:183], v[212:215], v[64:67]
	v_mfma_f32_16x16x32_bf16 v[72:75], v[170:173], v[212:215], v[72:75]
	s_barrier
	s_setprio 1
	s_mov_b32 m0, s30
	s_add_u32 s100, s42, 0x80
	s_addc_u32 s101, s43, 0
	s_add_u32 s8, s42, 0x40080
	ds_read_b128 v[184:187], v161 offset:49152
	ds_read_b128 v[188:191], v161 offset:50176
	ds_read_b128 v[192:195], v161 offset:51200
	ds_read_b128 v[196:199], v161 offset:52224
	ds_read_b128 v[200:203], v161 offset:53248
	ds_read_b128 v[204:207], v161 offset:54272
	ds_read_b128 v[208:211], v161 offset:55296
	ds_read_b128 v[212:215], v161 offset:56320
	global_load_lds_dwordx4 v132, s[100:101]
	s_mov_b32 m0, s31
	s_addc_u32 s9, s43, 0
	global_load_lds_dwordx4 v136, s[100:101]
	s_mov_b32 m0, s57
	s_nop 0
	global_load_lds_dwordx4 v132, s[8:9]
	s_mov_b32 m0, s96
	s_nop 0
	global_load_lds_dwordx4 v136, s[8:9]
	s_mov_b32 m0, s11
	s_nop 0
	global_load_lds_dwordx4 v130, s[24:25]
	s_mov_b32 m0, s19
	s_nop 0
	global_load_lds_dwordx4 v134, s[24:25]
	s_setprio 0
	s_waitcnt vmcnt(8)
	s_waitcnt lgkmcnt(0)
	s_barrier
	s_waitcnt lgkmcnt(0)
	v_mfma_f32_16x16x32_bf16 v[60:63], v[146:149], v[184:187], v[60:63]
	v_mfma_f32_16x16x32_bf16 v[52:55], v[154:157], v[184:187], v[52:55]
	v_mfma_f32_16x16x32_bf16 v[36:39], v[154:157], v[192:195], v[36:39]
	v_mfma_f32_16x16x32_bf16 v[44:47], v[146:149], v[192:195], v[44:47]
	v_mfma_f32_16x16x32_bf16 v[28:31], v[146:149], v[200:203], v[28:31]
	v_mfma_f32_16x16x32_bf16 v[20:23], v[154:157], v[200:203], v[20:23]
	v_mfma_f32_16x16x32_bf16 v[4:7], v[154:157], v[208:211], v[4:7]
	v_mfma_f32_16x16x32_bf16 v[12:15], v[146:149], v[208:211], v[12:15]
	v_mfma_f32_16x16x32_bf16 v[60:63], v[150:153], v[188:191], v[60:63]
	v_mfma_f32_16x16x32_bf16 v[52:55], v[162:165], v[188:191], v[52:55]
	v_mfma_f32_16x16x32_bf16 v[36:39], v[162:165], v[196:199], v[36:39]
	v_mfma_f32_16x16x32_bf16 v[44:47], v[150:153], v[196:199], v[44:47]
	v_mfma_f32_16x16x32_bf16 v[28:31], v[150:153], v[204:207], v[28:31]
	v_mfma_f32_16x16x32_bf16 v[20:23], v[162:165], v[204:207], v[20:23]
	v_mfma_f32_16x16x32_bf16 v[4:7], v[162:165], v[212:215], v[4:7]
	v_mfma_f32_16x16x32_bf16 v[12:15], v[150:153], v[212:215], v[12:15]
	v_mfma_f32_16x16x32_bf16 v[56:59], v[166:169], v[184:187], v[56:59]
	v_mfma_f32_16x16x32_bf16 v[48:51], v[174:177], v[184:187], v[48:51]
	v_mfma_f32_16x16x32_bf16 v[32:35], v[174:177], v[192:195], v[32:35]
	v_mfma_f32_16x16x32_bf16 v[40:43], v[166:169], v[192:195], v[40:43]
	v_mfma_f32_16x16x32_bf16 v[24:27], v[166:169], v[200:203], v[24:27]
	v_mfma_f32_16x16x32_bf16 v[16:19], v[174:177], v[200:203], v[16:19]
	v_mfma_f32_16x16x32_bf16 v[0:3], v[174:177], v[208:211], v[0:3]
	v_mfma_f32_16x16x32_bf16 v[8:11], v[166:169], v[208:211], v[8:11]
	v_mfma_f32_16x16x32_bf16 v[56:59], v[170:173], v[188:191], v[56:59]
	v_mfma_f32_16x16x32_bf16 v[48:51], v[180:183], v[188:191], v[48:51]
	v_mfma_f32_16x16x32_bf16 v[32:35], v[180:183], v[196:199], v[32:35]
	v_mfma_f32_16x16x32_bf16 v[40:43], v[170:173], v[196:199], v[40:43]
	v_mfma_f32_16x16x32_bf16 v[24:27], v[170:173], v[204:207], v[24:27]
	v_mfma_f32_16x16x32_bf16 v[16:19], v[180:183], v[204:207], v[16:19]
	v_mfma_f32_16x16x32_bf16 v[0:3], v[180:183], v[212:215], v[0:3]
	v_mfma_f32_16x16x32_bf16 v[8:11], v[170:173], v[212:215], v[8:11]
	s_barrier
	s_setprio 1
	s_add_i32 s18, s18, 2
	s_add_u32 s3, s3, 0x100
	s_addc_u32 s2, s2, 0
	s_add_u32 s0, s0, 0x800000
	s_addc_u32 s1, s1, 0
	s_cmp_gt_u32 s18, 13
	s_cbranch_scc0 .LBB0_161
	v_readlane_b32 s0, v255, 45
	v_readlane_b32 s1, v255, 46
	s_and_b64 vcc, exec, s[0:1]
	s_cbranch_vccz .LBB0_164
	s_barrier

; #define PG8_WAIT_V(n) asm volatile("s_waitcnt vmcnt(" #n ")" ::: "memory")
; #define PG8_BAR __builtin_amdgcn_s_barrier()
; template <class Epi, class Sched, bool ALIGN_EPI = false, bool SP2 = false>
; __device__ __forceinline__ void gemm_phase(PG8_LAS unsigned char* lds, const Gemm g, const Sched& S, const Epi& E) {
;     ...
;     PG8_WAIT_V(0);
;     if constexpr (!ALIGN_EPI) { if (wr == 0) PG8_BAR; }
;     PG8_BAR;
.LBB0_209:
	s_setprio 0
	s_waitcnt vmcnt(0)
	v_readlane_b32 s52, v254, 58
	v_readlane_b32 s38, v255, 19
	v_readlane_b32 s50, v254, 56
	v_readlane_b32 s53, v254, 59
	v_readlane_b32 s54, v255, 23
	v_readlane_b32 s96, v255, 35
	v_readlane_b32 s39, v255, 20
	v_readlane_b32 s19, v254, 48
	v_readlane_b32 s22, v254, 49
	v_readlane_b32 s23, v254, 50
	v_readlane_b32 s44, v254, 51
	v_readlane_b32 s45, v254, 52
	v_readlane_b32 s46, v254, 53
	v_readlane_b32 s47, v254, 54
	v_readlane_b32 s48, v254, 55
	v_readlane_b32 s51, v254, 57
	v_readlane_b32 s49, v254, 62
	s_mov_b32 s53, 0x409b43d5
	v_readlane_b32 s31, v255, 17
	v_readlane_b32 s55, v255, 24
	v_readlane_b32 s97, v255, 36
	s_barrier

; template <class Epi, class Sched, bool ALIGN_EPI = false, bool SP2 = false>
; __device__ __forceinline__ void gemm_phase(PG8_LAS unsigned char* lds, const Gemm g, const Sched& S, const Epi& E) {
;     ...
;         const bool has_next = S.next(ui + 1, nxt);
;         const char* nA = has_next ? (const char*)g.A + (size_t)nxt.pm * tstepA : cA; const char* nB = has_next ? (const char*)g.Bt + (size_t)nxt.pn * tstepB : cB;
;     ...
;         if constexpr (Epi::PEEL) {
;             const char* a1 = cA + kstepA; const char* a2 = cA + 2 * kstepA; const char* b2 = cB + 2 * kstepB; const char* a3 = a2 + kstepA; const char* b3 = b2 + kstepB;
;             PG8_ITER(8);
.LBB0_249:
	s_ashr_i32 s49, s48, 31
	s_lshl_b64 s[2:3], s[48:49], 15
	v_readlane_b32 s11, v255, 15
	s_add_u32 s50, s11, s2
	v_readlane_b32 s2, v255, 16
	s_addc_u32 s51, s2, s3
	s_ashr_i32 s47, s46, 31
	s_lshl_b64 s[2:3], s[46:47], 19
	s_add_u32 s52, s38, s2
	s_addc_u32 s53, s19, s3
	s_add_u32 s28, s42, 0x800000
	s_addc_u32 s29, s43, 0
	s_add_u32 s44, s42, 0xc00000
	s_addc_u32 s45, s43, 0
	s_add_i32 s99, 0, 0x10000
	s_and_b64 s[2:3], s[40:41], exec
	s_cselect_b32 s27, s51, s43
	s_cselect_b32 s47, s50, s42
	s_add_i32 vcc_hi, 0, 0x14000
	v_add_u32_e32 v130, s99, v97
	v_add_u32_e32 v131, vcc_hi, v97
	ds_read_b128 v[0:3], v130
	ds_read_b128 v[4:7], v130 offset:1024
	ds_read_b128 v[8:11], v130 offset:2048
	ds_read_b128 v[12:15], v130 offset:3072
	ds_read_b128 v[16:19], v131
	s_waitcnt lgkmcnt(0)
	ds_read_b128 v[20:23], v131 offset:1024
	ds_read_b128 v[24:27], v131 offset:2048
	ds_read_b128 v[28:31], v131 offset:3072
	s_and_b64 s[2:3], s[40:41], exec
	s_cselect_b32 s49, s53, s25
	s_cselect_b32 s54, s52, s24
	s_add_u32 s2, s42, 0x404000
	s_addc_u32 s3, s43, 0
	s_add_i32 s55, s22, 0xc000
	s_mov_b32 m0, s55
	s_add_i32 s98, s22, 0xe000
	ds_read_b128 v[32:35], v151
	ds_read_b128 v[36:39], v151 offset:1024
	ds_read_b128 v[40:43], v151 offset:2048
	ds_read_b128 v[44:47], v151 offset:3072
	ds_read_b128 v[48:51], v151 offset:4096
	ds_read_b128 v[52:55], v151 offset:5120
	ds_read_b128 v[56:59], v151 offset:6144
	ds_read_b128 v[60:63], v151 offset:7168
	global_load_lds_dwordx4 v134, s[2:3]
	s_mov_b32 m0, s98
	s_nop 0
	global_load_lds_dwordx4 v138, s[2:3]
	s_setprio 0
	s_waitcnt vmcnt(8)
	s_waitcnt lgkmcnt(0)
	s_barrier
	s_waitcnt lgkmcnt(0)
	v_mfma_f32_16x16x32_bf16 v[84:87], v[8:11], v[48:51], 0
	v_mfma_f32_16x16x32_bf16 v[88:91], v[12:15], v[52:55], v[84:87]
	v_mfma_f32_16x16x32_bf16 v[84:87], v[0:3], v[56:59], 0
	v_mfma_f32_16x16x32_bf16 v[64:67], v[0:3], v[32:35], 0
	v_mfma_f32_16x16x32_bf16 v[68:71], v[8:11], v[32:35], 0
	v_mfma_f32_16x16x32_bf16 v[72:75], v[0:3], v[40:43], 0
	v_mfma_f32_16x16x32_bf16 v[76:79], v[8:11], v[40:43], 0
	v_mfma_f32_16x16x32_bf16 v[80:83], v[0:3], v[48:51], 0
	v_mfma_f32_16x16x32_bf16 v[92:95], v[4:7], v[60:63], v[84:87]
	v_mfma_f32_16x16x32_bf16 v[84:87], v[8:11], v[56:59], 0
	v_mfma_f32_16x16x32_bf16 v[64:67], v[4:7], v[36:39], v[64:67]
	v_mfma_f32_16x16x32_bf16 v[68:71], v[12:15], v[36:39], v[68:71]
	v_mfma_f32_16x16x32_bf16 v[72:75], v[4:7], v[44:47], v[72:75]
	v_mfma_f32_16x16x32_bf16 v[76:79], v[12:15], v[44:47], v[76:79]
	v_mfma_f32_16x16x32_bf16 v[80:83], v[4:7], v[52:55], v[80:83]
	v_mfma_f32_16x16x32_bf16 v[106:109], v[12:15], v[60:63], v[84:87]
	v_mfma_f32_16x16x32_bf16 v[84:87], v[16:19], v[32:35], 0
	v_mfma_f32_16x16x32_bf16 v[32:35], v[24:27], v[32:35], 0
	v_mfma_f32_16x16x32_bf16 v[110:113], v[20:23], v[36:39], v[84:87]
	v_mfma_f32_16x16x32_bf16 v[32:35], v[28:31], v[36:39], v[32:35]
	v_mfma_f32_16x16x32_bf16 v[36:39], v[16:19], v[40:43], 0
	v_mfma_f32_16x16x32_bf16 v[40:43], v[24:27], v[40:43], 0
	v_mfma_f32_16x16x32_bf16 v[36:39], v[20:23], v[44:47], v[36:39]
	v_mfma_f32_16x16x32_bf16 v[40:43], v[28:31], v[44:47], v[40:43]
	v_mfma_f32_16x16x32_bf16 v[44:47], v[16:19], v[48:51], 0
	v_mfma_f32_16x16x32_bf16 v[48:51], v[24:27], v[48:51], 0
	v_mfma_f32_16x16x32_bf16 v[44:47], v[20:23], v[52:55], v[44:47]
	v_mfma_f32_16x16x32_bf16 v[48:51], v[28:31], v[52:55], v[48:51]
	v_mfma_f32_16x16x32_bf16 v[52:55], v[16:19], v[56:59], 0
	v_mfma_f32_16x16x32_bf16 v[56:59], v[24:27], v[56:59], 0
	v_mfma_f32_16x16x32_bf16 v[52:55], v[20:23], v[60:63], v[52:55]
	v_mfma_f32_16x16x32_bf16 v[56:59], v[28:31], v[60:63], v[56:59]
	s_barrier
	s_setprio 1
	v_lshl_add_u64 v[176:177], s[24:25], 0, v[136:137]
	s_mov_b64 s[2:3], 0x100
	s_add_i32 s99, s99, s10
	v_lshl_add_u64 v[132:133], v[176:177], 0, s[2:3]
	s_mov_b32 m0, s99
	v_lshl_add_u64 v[178:179], s[24:25], 0, v[140:141]
	s_add_i32 vcc_lo, s99, 0x2000
	ds_read_b128 v[60:63], v151 offset:16384
	ds_read_b128 v[84:87], v151 offset:17408
	ds_read_b128 v[98:101], v151 offset:18432
	ds_read_b128 v[102:105], v151 offset:19456
	ds_read_b128 v[114:117], v151 offset:20480
	ds_read_b128 v[118:121], v151 offset:21504
	ds_read_b128 v[122:125], v151 offset:22528
	ds_read_b128 v[126:129], v151 offset:23552
	global_load_lds_dwordx4 v[132:133], off
	v_lshl_add_u64 v[132:133], v[178:179], 0, s[2:3]
	s_add_u32 s2, s24, 0x40100
	s_mov_b32 m0, vcc_lo
	s_addc_u32 s3, s25, 0
	s_add_i32 vcc_hi, vcc_hi, s10
	global_load_lds_dwordx4 v[132:133], off
	s_mov_b32 m0, vcc_hi
	s_add_i32 s30, vcc_hi, 0x2000
	global_load_lds_dwordx4 v136, s[2:3]
	s_mov_b32 m0, s30
	s_mov_b64 s[34:35], 0x100
	global_load_lds_dwordx4 v140, s[2:3]
	s_mov_b32 m0, s22
	s_nop 0
	global_load_lds_dwordx4 v134, s[28:29]
	s_mov_b32 m0, s23
	s_nop 0
	global_load_lds_dwordx4 v138, s[28:29]
	s_setprio 0
	s_waitcnt vmcnt(8)
	s_waitcnt lgkmcnt(0)
	s_barrier
	s_waitcnt lgkmcnt(0)
	v_mfma_f32_16x16x32_bf16 v[146:149], v[0:3], v[60:63], 0
	v_mfma_f32_16x16x32_bf16 v[156:159], v[0:3], v[98:101], 0
	v_mfma_f32_16x16x32_bf16 v[164:167], v[0:3], v[114:117], 0
	v_mfma_f32_16x16x32_bf16 v[0:3], v[0:3], v[122:125], 0
	v_mfma_f32_16x16x32_bf16 v[146:149], v[4:7], v[84:87], v[146:149]
	v_mfma_f32_16x16x32_bf16 v[156:159], v[4:7], v[102:105], v[156:159]
	v_mfma_f32_16x16x32_bf16 v[164:167], v[4:7], v[118:121], v[164:167]
	v_mfma_f32_16x16x32_bf16 v[0:3], v[4:7], v[126:129], v[0:3]
	v_mfma_f32_16x16x32_bf16 v[4:7], v[8:11], v[122:125], 0
	v_mfma_f32_16x16x32_bf16 v[152:155], v[8:11], v[60:63], 0
	v_mfma_f32_16x16x32_bf16 v[160:163], v[8:11], v[98:101], 0
	v_mfma_f32_16x16x32_bf16 v[168:171], v[8:11], v[114:117], 0
	v_mfma_f32_16x16x32_bf16 v[8:11], v[12:15], v[126:129], v[4:7]
	v_mfma_f32_16x16x32_bf16 v[152:155], v[12:15], v[84:87], v[152:155]
	v_mfma_f32_16x16x32_bf16 v[160:163], v[12:15], v[102:105], v[160:163]
	v_mfma_f32_16x16x32_bf16 v[168:171], v[12:15], v[118:121], v[168:171]
	v_mfma_f32_16x16x32_bf16 v[4:7], v[16:19], v[60:63], 0
	v_mfma_f32_16x16x32_bf16 v[12:15], v[20:23], v[84:87], v[4:7]
	v_mfma_f32_16x16x32_bf16 v[4:7], v[24:27], v[60:63], 0
	v_mfma_f32_16x16x32_bf16 v[172:175], v[28:31], v[84:87], v[4:7]
	v_mfma_f32_16x16x32_bf16 v[4:7], v[16:19], v[98:101], 0
	v_mfma_f32_16x16x32_bf16 v[180:183], v[20:23], v[102:105], v[4:7]
	v_mfma_f32_16x16x32_bf16 v[4:7], v[24:27], v[98:101], 0
	v_mfma_f32_16x16x32_bf16 v[184:187], v[28:31], v[102:105], v[4:7]
	v_mfma_f32_16x16x32_bf16 v[4:7], v[16:19], v[114:117], 0
	v_mfma_f32_16x16x32_bf16 v[188:191], v[20:23], v[118:121], v[4:7]
	v_mfma_f32_16x16x32_bf16 v[4:7], v[24:27], v[114:117], 0
	v_mfma_f32_16x16x32_bf16 v[192:195], v[28:31], v[118:121], v[4:7]
	v_mfma_f32_16x16x32_bf16 v[4:7], v[16:19], v[122:125], 0
	v_mfma_f32_16x16x32_bf16 v[196:199], v[20:23], v[126:129], v[4:7]
	v_mfma_f32_16x16x32_bf16 v[4:7], v[24:27], v[122:125], 0
	v_mfma_f32_16x16x32_bf16 v[200:203], v[28:31], v[126:129], v[4:7]
	s_barrier
	s_setprio 1
	s_add_i32 s31, 0, 0x18000
	s_add_i32 s13, 0, 0x1c000
	v_add_u32_e32 v132, s31, v97
	v_add_u32_e32 v133, s13, v97
	s_nop 0
	ds_read_b128 v[4:7], v132
	ds_read_b128 v[24:27], v132 offset:1024
	ds_read_b128 v[28:31], v132 offset:2048
	ds_read_b128 v[60:63], v132 offset:3072
	ds_read_b128 v[204:207], v133
	ds_read_b128 v[208:211], v133 offset:1024
	ds_read_b128 v[212:215], v133 offset:2048
	ds_read_b128 v[216:219], v133 offset:3072
	s_add_u32 s2, s42, 0x804000
	s_addc_u32 s3, s43, 0
	s_mov_b32 m0, s39
	ds_read_b128 v[16:19], v151 offset:32768
	ds_read_b128 v[20:23], v151 offset:33792
	ds_read_b128 v[220:223], v151 offset:34816
	ds_read_b128 v[224:227], v151 offset:35840
	ds_read_b128 v[228:231], v151 offset:36864
	ds_read_b128 v[234:237], v151 offset:37888
	ds_read_b128 v[238:241], v151 offset:38912
	ds_read_b128 v[242:245], v151 offset:39936
	global_load_lds_dwordx4 v134, s[2:3]
	s_mov_b32 m0, s56
	s_nop 0
	global_load_lds_dwordx4 v138, s[2:3]
	s_setprio 0
	s_waitcnt vmcnt(8)
	s_waitcnt lgkmcnt(0)
	s_barrier
	s_waitcnt lgkmcnt(0)
	v_mfma_f32_16x16x32_bf16 v[64:67], v[4:7], v[16:19], v[64:67]
	v_mfma_f32_16x16x32_bf16 v[118:121], v[24:27], v[20:23], v[64:67]
	v_mfma_f32_16x16x32_bf16 v[64:67], v[28:31], v[16:19], v[68:71]
	v_mfma_f32_16x16x32_bf16 v[114:117], v[60:63], v[20:23], v[64:67]
	v_mfma_f32_16x16x32_bf16 v[64:67], v[4:7], v[220:223], v[72:75]
	v_mfma_f32_16x16x32_bf16 v[102:105], v[24:27], v[224:227], v[64:67]
	v_mfma_f32_16x16x32_bf16 v[64:67], v[28:31], v[220:223], v[76:79]
	v_mfma_f32_16x16x32_bf16 v[98:101], v[60:63], v[224:227], v[64:67]
	v_mfma_f32_16x16x32_bf16 v[64:67], v[4:7], v[228:231], v[80:83]
	v_mfma_f32_16x16x32_bf16 v[84:87], v[24:27], v[234:237], v[64:67]
	v_mfma_f32_16x16x32_bf16 v[64:67], v[28:31], v[228:231], v[88:91]
	v_mfma_f32_16x16x32_bf16 v[80:83], v[60:63], v[234:237], v[64:67]
	v_mfma_f32_16x16x32_bf16 v[64:67], v[4:7], v[238:241], v[92:95]
	v_mfma_f32_16x16x32_bf16 v[68:71], v[24:27], v[242:245], v[64:67]
	v_mfma_f32_16x16x32_bf16 v[64:67], v[28:31], v[238:241], v[106:109]
	v_mfma_f32_16x16x32_bf16 v[64:67], v[60:63], v[242:245], v[64:67]
	v_mfma_f32_16x16x32_bf16 v[72:75], v[204:207], v[16:19], v[110:113]
	v_mfma_f32_16x16x32_bf16 v[16:19], v[212:215], v[16:19], v[32:35]
	v_mfma_f32_16x16x32_bf16 v[122:125], v[216:219], v[20:23], v[16:19]
	v_mfma_f32_16x16x32_bf16 v[16:19], v[204:207], v[220:223], v[36:39]
	v_mfma_f32_16x16x32_bf16 v[110:113], v[208:211], v[224:227], v[16:19]
	v_mfma_f32_16x16x32_bf16 v[16:19], v[212:215], v[220:223], v[40:43]
	v_mfma_f32_16x16x32_bf16 v[106:109], v[216:219], v[224:227], v[16:19]
	v_mfma_f32_16x16x32_bf16 v[16:19], v[204:207], v[228:231], v[44:47]
	v_mfma_f32_16x16x32_bf16 v[92:95], v[208:211], v[234:237], v[16:19]
	v_mfma_f32_16x16x32_bf16 v[16:19], v[212:215], v[228:231], v[48:51]
	v_mfma_f32_16x16x32_bf16 v[88:91], v[216:219], v[234:237], v[16:19]
	v_mfma_f32_16x16x32_bf16 v[16:19], v[204:207], v[238:241], v[52:55]
	v_mfma_f32_16x16x32_bf16 v[76:79], v[208:211], v[242:245], v[16:19]
	v_mfma_f32_16x16x32_bf16 v[16:19], v[212:215], v[238:241], v[56:59]
	v_mfma_f32_16x16x32_bf16 v[126:129], v[208:211], v[20:23], v[72:75]
	v_mfma_f32_16x16x32_bf16 v[72:75], v[216:219], v[242:245], v[16:19]
	s_barrier
; template <class Epi, class Sched, bool ALIGN_EPI = false, bool SP2 = false>
; __device__ __forceinline__ void gemm_phase(PG8_LAS unsigned char* lds, const Gemm g, const Sched& S, const Epi& E) {
;     ...
;             const bool last = (t == nt - 2);
;             const char* a1 = cA + (size_t)(t + 1) * kstepA;
;             const char* a2 = last ? nA : cA + (size_t)(t + 2) * kstepA; const char* b2 = last ? nB : cB + (size_t)(t + 2) * kstepB;
	s_setprio 1
	s_mov_b64 s[2:3], 0x180
	s_add_i32 s31, s31, s10
	s_nop 1
	v_lshl_add_u64 v[16:17], v[176:177], 0, s[2:3]
	s_mov_b32 m0, s31
	s_add_i32 s12, s31, 0x2000
	ds_read_b128 v[40:43], v151 offset:49152
	ds_read_b128 v[44:47], v151 offset:50176
	ds_read_b128 v[220:223], v151 offset:51200
	ds_read_b128 v[224:227], v151 offset:52224
	ds_read_b128 v[228:231], v151 offset:53248
	ds_read_b128 v[234:237], v151 offset:54272
	ds_read_b128 v[238:241], v151 offset:55296
	ds_read_b128 v[242:245], v151 offset:56320
	global_load_lds_dwordx4 v[16:17], off
	v_lshl_add_u64 v[16:17], v[178:179], 0, s[2:3]
	s_add_u32 s2, s24, 0x40180
	s_mov_b32 m0, s12
	s_addc_u32 s3, s25, 0
	s_add_i32 s13, s13, s10
	global_load_lds_dwordx4 v[16:17], off
	s_mov_b32 m0, s13
	s_add_i32 s11, s13, 0x2000
	global_load_lds_dwordx4 v136, s[2:3]
	s_mov_b32 m0, s11
	s_nop 0
	global_load_lds_dwordx4 v140, s[2:3]
	s_mov_b32 m0, s59
	s_nop 0
	global_load_lds_dwordx4 v134, s[44:45]
	s_mov_b32 m0, s96
	s_nop 0
	global_load_lds_dwordx4 v138, s[44:45]
	s_setprio 0
	s_waitcnt vmcnt(8)
	s_waitcnt lgkmcnt(0)
	s_barrier
	s_waitcnt lgkmcnt(0)
	v_mfma_f32_16x16x32_bf16 v[16:19], v[4:7], v[40:43], v[146:149]
	v_mfma_f32_16x16x32_bf16 v[52:55], v[24:27], v[44:47], v[16:19]
	v_mfma_f32_16x16x32_bf16 v[16:19], v[28:31], v[40:43], v[152:155]
	v_mfma_f32_16x16x32_bf16 v[48:51], v[60:63], v[44:47], v[16:19]
	v_mfma_f32_16x16x32_bf16 v[16:19], v[4:7], v[220:223], v[156:159]
	v_mfma_f32_16x16x32_bf16 v[36:39], v[24:27], v[224:227], v[16:19]
	v_mfma_f32_16x16x32_bf16 v[16:19], v[28:31], v[220:223], v[160:163]
	v_mfma_f32_16x16x32_bf16 v[32:35], v[60:63], v[224:227], v[16:19]
	v_mfma_f32_16x16x32_bf16 v[16:19], v[4:7], v[228:231], v[164:167]
	v_mfma_f32_16x16x32_bf16 v[0:3], v[4:7], v[238:241], v[0:3]
	v_mfma_f32_16x16x32_bf16 v[20:23], v[24:27], v[234:237], v[16:19]
	v_mfma_f32_16x16x32_bf16 v[16:19], v[28:31], v[228:231], v[168:171]
	v_mfma_f32_16x16x32_bf16 v[4:7], v[24:27], v[242:245], v[0:3]
	v_mfma_f32_16x16x32_bf16 v[0:3], v[28:31], v[238:241], v[8:11]
	v_mfma_f32_16x16x32_bf16 v[16:19], v[60:63], v[234:237], v[16:19]
	v_mfma_f32_16x16x32_bf16 v[0:3], v[60:63], v[242:245], v[0:3]
	v_mfma_f32_16x16x32_bf16 v[8:11], v[204:207], v[40:43], v[12:15]
	v_mfma_f32_16x16x32_bf16 v[60:63], v[208:211], v[44:47], v[8:11]
	v_mfma_f32_16x16x32_bf16 v[8:11], v[212:215], v[40:43], v[172:175]
	v_mfma_f32_16x16x32_bf16 v[56:59], v[216:219], v[44:47], v[8:11]
	v_mfma_f32_16x16x32_bf16 v[8:11], v[204:207], v[220:223], v[180:183]
	v_mfma_f32_16x16x32_bf16 v[44:47], v[208:211], v[224:227], v[8:11]
	v_mfma_f32_16x16x32_bf16 v[8:11], v[212:215], v[220:223], v[184:187]
	v_mfma_f32_16x16x32_bf16 v[40:43], v[216:219], v[224:227], v[8:11]
	v_mfma_f32_16x16x32_bf16 v[8:11], v[204:207], v[228:231], v[188:191]
	v_mfma_f32_16x16x32_bf16 v[28:31], v[208:211], v[234:237], v[8:11]
	v_mfma_f32_16x16x32_bf16 v[8:11], v[212:215], v[228:231], v[192:195]
	v_mfma_f32_16x16x32_bf16 v[24:27], v[216:219], v[234:237], v[8:11]
	v_mfma_f32_16x16x32_bf16 v[8:11], v[204:207], v[238:241], v[196:199]
	v_mfma_f32_16x16x32_bf16 v[12:15], v[208:211], v[242:245], v[8:11]
	v_mfma_f32_16x16x32_bf16 v[8:11], v[212:215], v[238:241], v[200:203]
	v_mfma_f32_16x16x32_bf16 v[8:11], v[216:219], v[242:245], v[8:11]
	s_barrier
	s_setprio 1
	s_add_u32 s3, s24, 0x200
	s_addc_u32 s2, s25, 0
	s_add_u32 s24, s42, 0xc04000
	s_addc_u32 s25, s43, 0
	s_mov_b32 s18, 0
.LBB0_250:
	ds_read_b128 v[146:149], v130
	ds_read_b128 v[152:155], v130 offset:1024
	ds_read_b128 v[156:159], v130 offset:2048
	ds_read_b128 v[160:163], v130 offset:3072
	ds_read_b128 v[164:167], v131
	ds_read_b128 v[168:171], v131 offset:1024
	ds_read_b128 v[172:175], v131 offset:2048
	ds_read_b128 v[180:183], v131 offset:3072
	s_add_u32 s16, s24, 0x3fc000
	s_addc_u32 s17, s25, 0
	s_cmp_eq_u32 s18, 12
	s_cselect_b32 s28, s47, s16
	s_cselect_b32 s29, s27, s17
	s_cselect_b32 s44, s54, s3
	s_cselect_b32 s45, s49, s2
	s_add_u32 s42, s28, 0x400000
	s_addc_u32 s43, s29, 0
	s_mov_b32 m0, s55
	ds_read_b128 v[184:187], v151
	ds_read_b128 v[188:191], v151 offset:1024
	ds_read_b128 v[192:195], v151 offset:2048
	ds_read_b128 v[196:199], v151 offset:3072
	ds_read_b128 v[200:203], v151 offset:4096
	ds_read_b128 v[204:207], v151 offset:5120
	ds_read_b128 v[208:211], v151 offset:6144
	ds_read_b128 v[212:215], v151 offset:7168
	global_load_lds_dwordx4 v144, s[24:25]
	s_mov_b32 m0, s98
	s_nop 0
	global_load_lds_dwordx4 v142, s[24:25]
	s_setprio 0
	s_waitcnt vmcnt(8)
	s_waitcnt lgkmcnt(0)
	s_barrier
	s_waitcnt lgkmcnt(0)
	v_mfma_f32_16x16x32_bf16 v[118:121], v[146:149], v[184:187], v[118:121]
	v_mfma_f32_16x16x32_bf16 v[114:117], v[156:159], v[184:187], v[114:117]
	v_mfma_f32_16x16x32_bf16 v[98:101], v[156:159], v[192:195], v[98:101]
	v_mfma_f32_16x16x32_bf16 v[102:105], v[146:149], v[192:195], v[102:105]
	v_mfma_f32_16x16x32_bf16 v[84:87], v[146:149], v[200:203], v[84:87]
	v_mfma_f32_16x16x32_bf16 v[80:83], v[156:159], v[200:203], v[80:83]
	v_mfma_f32_16x16x32_bf16 v[64:67], v[156:159], v[208:211], v[64:67]
	v_mfma_f32_16x16x32_bf16 v[68:71], v[146:149], v[208:211], v[68:71]
	v_mfma_f32_16x16x32_bf16 v[118:121], v[152:155], v[188:191], v[118:121]
	v_mfma_f32_16x16x32_bf16 v[114:117], v[160:163], v[188:191], v[114:117]
	v_mfma_f32_16x16x32_bf16 v[98:101], v[160:163], v[196:199], v[98:101]
	v_mfma_f32_16x16x32_bf16 v[102:105], v[152:155], v[196:199], v[102:105]
	v_mfma_f32_16x16x32_bf16 v[84:87], v[152:155], v[204:207], v[84:87]
	v_mfma_f32_16x16x32_bf16 v[80:83], v[160:163], v[204:207], v[80:83]
	v_mfma_f32_16x16x32_bf16 v[64:67], v[160:163], v[212:215], v[64:67]
	v_mfma_f32_16x16x32_bf16 v[68:71], v[152:155], v[212:215], v[68:71]
	v_mfma_f32_16x16x32_bf16 v[126:129], v[164:167], v[184:187], v[126:129]
	v_mfma_f32_16x16x32_bf16 v[122:125], v[172:175], v[184:187], v[122:125]
	v_mfma_f32_16x16x32_bf16 v[106:109], v[172:175], v[192:195], v[106:109]
	v_mfma_f32_16x16x32_bf16 v[110:113], v[164:167], v[192:195], v[110:113]
	v_mfma_f32_16x16x32_bf16 v[92:95], v[164:167], v[200:203], v[92:95]
	v_mfma_f32_16x16x32_bf16 v[88:91], v[172:175], v[200:203], v[88:91]
	v_mfma_f32_16x16x32_bf16 v[72:75], v[172:175], v[208:211], v[72:75]
	v_mfma_f32_16x16x32_bf16 v[76:79], v[164:167], v[208:211], v[76:79]
	v_mfma_f32_16x16x32_bf16 v[126:129], v[168:171], v[188:191], v[126:129]
	v_mfma_f32_16x16x32_bf16 v[122:125], v[180:183], v[188:191], v[122:125]
	v_mfma_f32_16x16x32_bf16 v[106:109], v[180:183], v[196:199], v[106:109]
	v_mfma_f32_16x16x32_bf16 v[110:113], v[168:171], v[196:199], v[110:113]
	v_mfma_f32_16x16x32_bf16 v[92:95], v[168:171], v[204:207], v[92:95]
	v_mfma_f32_16x16x32_bf16 v[88:91], v[180:183], v[204:207], v[88:91]
	v_mfma_f32_16x16x32_bf16 v[72:75], v[180:183], v[212:215], v[72:75]
	v_mfma_f32_16x16x32_bf16 v[76:79], v[168:171], v[212:215], v[76:79]
	s_barrier
	s_setprio 1
	s_mov_b32 m0, s99
	s_add_u32 s16, s44, 0x40000
	ds_read_b128 v[184:187], v151 offset:16384
	ds_read_b128 v[188:191], v151 offset:17408
	ds_read_b128 v[192:195], v151 offset:18432
	ds_read_b128 v[196:199], v151 offset:19456
	ds_read_b128 v[200:203], v151 offset:20480
	ds_read_b128 v[204:207], v151 offset:21504
	ds_read_b128 v[208:211], v151 offset:22528
	ds_read_b128 v[212:215], v151 offset:23552
	global_load_lds_dwordx4 v136, s[44:45]
	s_mov_b32 m0, vcc_lo
	s_addc_u32 s17, s45, 0
	global_load_lds_dwordx4 v140, s[44:45]
	s_mov_b32 m0, vcc_hi
	s_nop 0
	global_load_lds_dwordx4 v136, s[16:17]
	s_mov_b32 m0, s30
	s_nop 0
	global_load_lds_dwordx4 v140, s[16:17]
	s_mov_b32 m0, s22
	s_nop 0
	global_load_lds_dwordx4 v134, s[28:29]
	s_mov_b32 m0, s23
	s_nop 0
	global_load_lds_dwordx4 v138, s[28:29]
	s_setprio 0
	s_waitcnt vmcnt(8)
	s_waitcnt lgkmcnt(0)
	s_barrier
	s_waitcnt lgkmcnt(0)
	v_mfma_f32_16x16x32_bf16 v[52:55], v[146:149], v[184:187], v[52:55]
	v_mfma_f32_16x16x32_bf16 v[48:51], v[156:159], v[184:187], v[48:51]
	v_mfma_f32_16x16x32_bf16 v[32:35], v[156:159], v[192:195], v[32:35]
	v_mfma_f32_16x16x32_bf16 v[36:39], v[146:149], v[192:195], v[36:39]
	v_mfma_f32_16x16x32_bf16 v[20:23], v[146:149], v[200:203], v[20:23]
	v_mfma_f32_16x16x32_bf16 v[16:19], v[156:159], v[200:203], v[16:19]
	v_mfma_f32_16x16x32_bf16 v[0:3], v[156:159], v[208:211], v[0:3]
	v_mfma_f32_16x16x32_bf16 v[4:7], v[146:149], v[208:211], v[4:7]
	v_mfma_f32_16x16x32_bf16 v[52:55], v[152:155], v[188:191], v[52:55]
	v_mfma_f32_16x16x32_bf16 v[48:51], v[160:163], v[188:191], v[48:51]
	v_mfma_f32_16x16x32_bf16 v[32:35], v[160:163], v[196:199], v[32:35]
	v_mfma_f32_16x16x32_bf16 v[36:39], v[152:155], v[196:199], v[36:39]
	v_mfma_f32_16x16x32_bf16 v[20:23], v[152:155], v[204:207], v[20:23]
	v_mfma_f32_16x16x32_bf16 v[16:19], v[160:163], v[204:207], v[16:19]
	v_mfma_f32_16x16x32_bf16 v[0:3], v[160:163], v[212:215], v[0:3]
	v_mfma_f32_16x16x32_bf16 v[4:7], v[152:155], v[212:215], v[4:7]
	v_mfma_f32_16x16x32_bf16 v[60:63], v[164:167], v[184:187], v[60:63]
	v_mfma_f32_16x16x32_bf16 v[56:59], v[172:175], v[184:187], v[56:59]
	v_mfma_f32_16x16x32_bf16 v[40:43], v[172:175], v[192:195], v[40:43]
	v_mfma_f32_16x16x32_bf16 v[44:47], v[164:167], v[192:195], v[44:47]
	v_mfma_f32_16x16x32_bf16 v[28:31], v[164:167], v[200:203], v[28:31]
	v_mfma_f32_16x16x32_bf16 v[24:27], v[172:175], v[200:203], v[24:27]
	v_mfma_f32_16x16x32_bf16 v[8:11], v[172:175], v[208:211], v[8:11]
	v_mfma_f32_16x16x32_bf16 v[12:15], v[164:167], v[208:211], v[12:15]
	v_mfma_f32_16x16x32_bf16 v[60:63], v[168:171], v[188:191], v[60:63]
	v_mfma_f32_16x16x32_bf16 v[56:59], v[180:183], v[188:191], v[56:59]
	v_mfma_f32_16x16x32_bf16 v[40:43], v[180:183], v[196:199], v[40:43]
	v_mfma_f32_16x16x32_bf16 v[44:47], v[168:171], v[196:199], v[44:47]
	v_mfma_f32_16x16x32_bf16 v[28:31], v[168:171], v[204:207], v[28:31]
	v_mfma_f32_16x16x32_bf16 v[24:27], v[180:183], v[204:207], v[24:27]
	v_mfma_f32_16x16x32_bf16 v[8:11], v[180:183], v[212:215], v[8:11]
	v_mfma_f32_16x16x32_bf16 v[12:15], v[168:171], v[212:215], v[12:15]
	s_barrier
; #define PG8_BAR __builtin_amdgcn_s_barrier()
; template <class Epi, class Sched, bool ALIGN_EPI = false, bool SP2 = false>
; __device__ __forceinline__ void gemm_phase(PG8_LAS unsigned char* lds, const Gemm g, const Sched& S, const Epi& E) {
;     ...
;         for (int t = (Epi::PEEL ? 2 : 0); t < nt; t += 2) {
;             const bool last = (t == nt - 2);
;             const char* a1 = cA + (size_t)(t + 1) * kstepA;
;             const char* a2 = last ? nA : cA + (size_t)(t + 2) * kstepA; const char* b2 = last ? nB : cB + (size_t)(t + 2) * kstepB;
;             const char* a3 = a2 + kstepA; const char* b3 = b2 + kstepB;
;             PG8_ITER(8);
;         }
;     ...
;         if constexpr (ALIGN_EPI) { if (wr == 0) PG8_BAR; }
	s_setprio 1
	ds_read_b128 v[146:149], v132
	ds_read_b128 v[152:155], v132 offset:1024
	ds_read_b128 v[156:159], v132 offset:2048
	ds_read_b128 v[160:163], v132 offset:3072
	ds_read_b128 v[164:167], v133
	ds_read_b128 v[168:171], v133 offset:1024
	ds_read_b128 v[172:175], v133 offset:2048
	ds_read_b128 v[180:183], v133 offset:3072
	s_add_u32 s16, s28, 0x4000
	s_addc_u32 s17, s29, 0
	s_mov_b32 m0, s39
	ds_read_b128 v[184:187], v151 offset:32768
	ds_read_b128 v[188:191], v151 offset:33792
	ds_read_b128 v[192:195], v151 offset:34816
	ds_read_b128 v[196:199], v151 offset:35840
	ds_read_b128 v[200:203], v151 offset:36864
	ds_read_b128 v[204:207], v151 offset:37888
	ds_read_b128 v[208:211], v151 offset:38912
	ds_read_b128 v[212:215], v151 offset:39936
	global_load_lds_dwordx4 v134, s[16:17]
	s_mov_b32 m0, s56
	s_nop 0
	global_load_lds_dwordx4 v138, s[16:17]
	s_setprio 0
	s_waitcnt vmcnt(8)
	s_waitcnt lgkmcnt(0)
	s_barrier
	s_waitcnt lgkmcnt(0)
	v_mfma_f32_16x16x32_bf16 v[118:121], v[146:149], v[184:187], v[118:121]
	v_mfma_f32_16x16x32_bf16 v[114:117], v[156:159], v[184:187], v[114:117]
	v_mfma_f32_16x16x32_bf16 v[98:101], v[156:159], v[192:195], v[98:101]
	v_mfma_f32_16x16x32_bf16 v[102:105], v[146:149], v[192:195], v[102:105]
	v_mfma_f32_16x16x32_bf16 v[84:87], v[146:149], v[200:203], v[84:87]
	v_mfma_f32_16x16x32_bf16 v[80:83], v[156:159], v[200:203], v[80:83]
	v_mfma_f32_16x16x32_bf16 v[64:67], v[156:159], v[208:211], v[64:67]
	v_mfma_f32_16x16x32_bf16 v[68:71], v[146:149], v[208:211], v[68:71]
	v_mfma_f32_16x16x32_bf16 v[118:121], v[152:155], v[188:191], v[118:121]
	v_mfma_f32_16x16x32_bf16 v[114:117], v[160:163], v[188:191], v[114:117]
	v_mfma_f32_16x16x32_bf16 v[98:101], v[160:163], v[196:199], v[98:101]
	v_mfma_f32_16x16x32_bf16 v[102:105], v[152:155], v[196:199], v[102:105]
	v_mfma_f32_16x16x32_bf16 v[84:87], v[152:155], v[204:207], v[84:87]
	v_mfma_f32_16x16x32_bf16 v[80:83], v[160:163], v[204:207], v[80:83]
	v_mfma_f32_16x16x32_bf16 v[64:67], v[160:163], v[212:215], v[64:67]
	v_mfma_f32_16x16x32_bf16 v[68:71], v[152:155], v[212:215], v[68:71]
	v_mfma_f32_16x16x32_bf16 v[126:129], v[164:167], v[184:187], v[126:129]
	v_mfma_f32_16x16x32_bf16 v[122:125], v[172:175], v[184:187], v[122:125]
	v_mfma_f32_16x16x32_bf16 v[106:109], v[172:175], v[192:195], v[106:109]
	v_mfma_f32_16x16x32_bf16 v[110:113], v[164:167], v[192:195], v[110:113]
	v_mfma_f32_16x16x32_bf16 v[92:95], v[164:167], v[200:203], v[92:95]
	v_mfma_f32_16x16x32_bf16 v[88:91], v[172:175], v[200:203], v[88:91]
	v_mfma_f32_16x16x32_bf16 v[72:75], v[172:175], v[208:211], v[72:75]
	v_mfma_f32_16x16x32_bf16 v[76:79], v[164:167], v[208:211], v[76:79]
	v_mfma_f32_16x16x32_bf16 v[126:129], v[168:171], v[188:191], v[126:129]
	v_mfma_f32_16x16x32_bf16 v[122:125], v[180:183], v[188:191], v[122:125]
	v_mfma_f32_16x16x32_bf16 v[106:109], v[180:183], v[196:199], v[106:109]
	v_mfma_f32_16x16x32_bf16 v[110:113], v[168:171], v[196:199], v[110:113]
	v_mfma_f32_16x16x32_bf16 v[92:95], v[168:171], v[204:207], v[92:95]
	v_mfma_f32_16x16x32_bf16 v[88:91], v[180:183], v[204:207], v[88:91]
	v_mfma_f32_16x16x32_bf16 v[72:75], v[180:183], v[212:215], v[72:75]
	v_mfma_f32_16x16x32_bf16 v[76:79], v[168:171], v[212:215], v[76:79]
	s_barrier
	s_setprio 1
	s_mov_b32 m0, s31
	s_add_u32 s100, s44, 0x80
	s_addc_u32 s101, s45, 0
	s_add_u32 s16, s44, 0x40080
	ds_read_b128 v[184:187], v151 offset:49152
	ds_read_b128 v[188:191], v151 offset:50176
	ds_read_b128 v[192:195], v151 offset:51200
	ds_read_b128 v[196:199], v151 offset:52224
	ds_read_b128 v[200:203], v151 offset:53248
	ds_read_b128 v[204:207], v151 offset:54272
	ds_read_b128 v[208:211], v151 offset:55296
	ds_read_b128 v[212:215], v151 offset:56320
	global_load_lds_dwordx4 v136, s[100:101]
	s_mov_b32 m0, s12
	s_addc_u32 s17, s45, 0
	global_load_lds_dwordx4 v140, s[100:101]
	s_mov_b32 m0, s13
	s_nop 0
	global_load_lds_dwordx4 v136, s[16:17]
	s_mov_b32 m0, s11
	s_nop 0
	global_load_lds_dwordx4 v140, s[16:17]
	s_mov_b32 m0, s59
	s_nop 0
	global_load_lds_dwordx4 v134, s[42:43]
	s_mov_b32 m0, s96
	s_nop 0
	global_load_lds_dwordx4 v138, s[42:43]
	s_setprio 0
	s_waitcnt vmcnt(8)
	s_waitcnt lgkmcnt(0)
	s_barrier
	s_waitcnt lgkmcnt(0)
	v_mfma_f32_16x16x32_bf16 v[52:55], v[146:149], v[184:187], v[52:55]
	v_mfma_f32_16x16x32_bf16 v[48:51], v[156:159], v[184:187], v[48:51]
	v_mfma_f32_16x16x32_bf16 v[32:35], v[156:159], v[192:195], v[32:35]
	v_mfma_f32_16x16x32_bf16 v[36:39], v[146:149], v[192:195], v[36:39]
	v_mfma_f32_16x16x32_bf16 v[20:23], v[146:149], v[200:203], v[20:23]
	v_mfma_f32_16x16x32_bf16 v[16:19], v[156:159], v[200:203], v[16:19]
	v_mfma_f32_16x16x32_bf16 v[0:3], v[156:159], v[208:211], v[0:3]
	v_mfma_f32_16x16x32_bf16 v[4:7], v[146:149], v[208:211], v[4:7]
	v_mfma_f32_16x16x32_bf16 v[52:55], v[152:155], v[188:191], v[52:55]
	v_mfma_f32_16x16x32_bf16 v[48:51], v[160:163], v[188:191], v[48:51]
	v_mfma_f32_16x16x32_bf16 v[32:35], v[160:163], v[196:199], v[32:35]
	v_mfma_f32_16x16x32_bf16 v[36:39], v[152:155], v[196:199], v[36:39]
	v_mfma_f32_16x16x32_bf16 v[20:23], v[152:155], v[204:207], v[20:23]
	v_mfma_f32_16x16x32_bf16 v[16:19], v[160:163], v[204:207], v[16:19]
	v_mfma_f32_16x16x32_bf16 v[0:3], v[160:163], v[212:215], v[0:3]
	v_mfma_f32_16x16x32_bf16 v[4:7], v[152:155], v[212:215], v[4:7]
	v_mfma_f32_16x16x32_bf16 v[60:63], v[164:167], v[184:187], v[60:63]
	v_mfma_f32_16x16x32_bf16 v[56:59], v[172:175], v[184:187], v[56:59]
	v_mfma_f32_16x16x32_bf16 v[40:43], v[172:175], v[192:195], v[40:43]
	v_mfma_f32_16x16x32_bf16 v[44:47], v[164:167], v[192:195], v[44:47]
	v_mfma_f32_16x16x32_bf16 v[28:31], v[164:167], v[200:203], v[28:31]
	v_mfma_f32_16x16x32_bf16 v[24:27], v[172:175], v[200:203], v[24:27]
	v_mfma_f32_16x16x32_bf16 v[8:11], v[172:175], v[208:211], v[8:11]
	v_mfma_f32_16x16x32_bf16 v[12:15], v[164:167], v[208:211], v[12:15]
	v_mfma_f32_16x16x32_bf16 v[60:63], v[168:171], v[188:191], v[60:63]
	v_mfma_f32_16x16x32_bf16 v[56:59], v[180:183], v[188:191], v[56:59]
	v_mfma_f32_16x16x32_bf16 v[40:43], v[180:183], v[196:199], v[40:43]
	v_mfma_f32_16x16x32_bf16 v[44:47], v[168:171], v[196:199], v[44:47]
	v_mfma_f32_16x16x32_bf16 v[28:31], v[168:171], v[204:207], v[28:31]
	v_mfma_f32_16x16x32_bf16 v[24:27], v[180:183], v[204:207], v[24:27]
	v_mfma_f32_16x16x32_bf16 v[8:11], v[180:183], v[212:215], v[8:11]
	v_mfma_f32_16x16x32_bf16 v[12:15], v[168:171], v[212:215], v[12:15]
	s_barrier
	s_setprio 1
	s_add_i32 s18, s18, 2
	s_add_u32 s3, s3, 0x100
	s_addc_u32 s2, s2, 0
	s_add_u32 s24, s24, 0x800000
	s_addc_u32 s25, s25, 0
	s_cmp_gt_u32 s18, 13
	s_cbranch_scc0 .LBB0_250
	v_readlane_b32 s2, v255, 33
	v_readlane_b32 s3, v255, 34
	v_readlane_b32 s12, v255, 31
	s_and_b64 vcc, exec, s[2:3]
	v_readlane_b32 s13, v255, 32
	s_cbranch_vccz .LBB0_253
	s_barrier

; #define PG8_WAIT_V(n) asm volatile("s_waitcnt vmcnt(" #n ")" ::: "memory")
; #define PG8_BAR __builtin_amdgcn_s_barrier()
; template <class Epi, class Sched, bool ALIGN_EPI = false, bool SP2 = false>
; __device__ __forceinline__ void gemm_phase(PG8_LAS unsigned char* lds, const Gemm g, const Sched& S, const Epi& E) {
;     ...
;     PG8_WAIT_V(0);
;     if constexpr (!ALIGN_EPI) { if (wr == 0) PG8_BAR; }
;     PG8_BAR;
.LBB0_322:
	s_setprio 0
	s_waitcnt vmcnt(0)
	v_readlane_b32 s52, v254, 58
	v_readlane_b32 s38, v255, 19
	v_readlane_b32 s50, v254, 56
	v_readlane_b32 s53, v254, 59
	v_readlane_b32 s56, v254, 60
	v_readlane_b32 s96, v255, 35
	v_readlane_b32 s39, v255, 20
	v_readlane_b32 s19, v254, 48
	v_readlane_b32 s22, v254, 49
	v_readlane_b32 s23, v254, 50
	v_readlane_b32 s44, v254, 51
	v_readlane_b32 s45, v254, 52
	v_readlane_b32 s46, v254, 53
	v_readlane_b32 s47, v254, 54
	v_readlane_b32 s48, v254, 55
	v_readlane_b32 s51, v254, 57
	v_readlane_b32 s57, v254, 61
	v_readlane_b32 s49, v254, 62
	s_mov_b32 s53, 0x409b43d5
	v_readlane_b32 s31, v255, 17
	v_readlane_b32 s97, v255, 36
	s_barrier

; template <class Epi, class Sched, bool ALIGN_EPI = false, bool SP2 = false>
; __device__ __forceinline__ void gemm_phase(PG8_LAS unsigned char* lds, const Gemm g, const Sched& S, const Epi& E) {
;     ...
;         for (int t = (Epi::PEEL ? 2 : 0); t < nt; t += 2) {
;             const bool last = (t == nt - 2);
;             const char* a1 = cA + (size_t)(t + 1) * kstepA;
;             const char* a2 = last ? nA : cA + (size_t)(t + 2) * kstepA; const char* b2 = last ? nB : cB + (size_t)(t + 2) * kstepB;
;             const char* a3 = a2 + kstepA; const char* b3 = b2 + kstepB;
;             PG8_ITER(8);
.LBB0_345:
	s_add_i32 s10, s10, 2
	s_add_u32 s44, s42, s34
	s_addc_u32 s45, s43, s35
	s_add_i32 s18, 0, 0x10000
	s_and_b64 s[2:3], exec, s[46:47]
	s_cselect_b32 s3, s13, s59
	s_cselect_b32 s2, s12, s58
	s_add_i32 s38, 0, 0x14000
	v_add_u32_e32 v142, s18, v97
	v_add_u32_e32 v170, s38, v97
	ds_read_b128 v[122:125], v142
	ds_read_b128 v[126:129], v142 offset:1024
	ds_read_b128 v[138:141], v142 offset:2048
	ds_read_b128 v[142:145], v142 offset:3072
	ds_read_b128 v[146:149], v170
	ds_read_b128 v[150:153], v170 offset:1024
	ds_read_b128 v[154:157], v170 offset:2048
	ds_read_b128 v[170:173], v170 offset:3072
	s_add_i32 m0, s97, 0xc000
	ds_read_b128 v[174:177], v188
	ds_read_b128 v[180:183], v188 offset:1024
	ds_read_b128 v[184:187], v188 offset:2048
	ds_read_b128 v[190:193], v188 offset:3072
	ds_read_b128 v[194:197], v188 offset:4096
	ds_read_b128 v[198:201], v188 offset:5120
	ds_read_b128 v[202:205], v188 offset:6144
	ds_read_b128 v[206:209], v188 offset:7168
	global_load_lds_dwordx4 v168, s[24:25]
	s_add_i32 m0, s97, 0xe000
	s_nop 0
	global_load_lds_dwordx4 v166, s[24:25]
	s_setprio 0
	s_waitcnt vmcnt(8)
	s_waitcnt lgkmcnt(0)
	s_barrier
	s_waitcnt lgkmcnt(0)
	v_mfma_f32_16x16x32_bf16 v[134:137], v[122:125], v[174:177], v[134:137]
	v_mfma_f32_16x16x32_bf16 v[130:133], v[138:141], v[174:177], v[130:133]
	v_mfma_f32_16x16x32_bf16 v[106:109], v[138:141], v[184:187], v[106:109]
	v_mfma_f32_16x16x32_bf16 v[110:113], v[122:125], v[184:187], v[110:113]
	v_mfma_f32_16x16x32_bf16 v[92:95], v[122:125], v[194:197], v[92:95]
	v_mfma_f32_16x16x32_bf16 v[88:91], v[138:141], v[194:197], v[88:91]
	v_mfma_f32_16x16x32_bf16 v[72:75], v[138:141], v[202:205], v[72:75]
	v_mfma_f32_16x16x32_bf16 v[76:79], v[122:125], v[202:205], v[76:79]
	v_mfma_f32_16x16x32_bf16 v[134:137], v[126:129], v[180:183], v[134:137]
	v_mfma_f32_16x16x32_bf16 v[130:133], v[142:145], v[180:183], v[130:133]
	v_mfma_f32_16x16x32_bf16 v[106:109], v[142:145], v[190:193], v[106:109]
	v_mfma_f32_16x16x32_bf16 v[110:113], v[126:129], v[190:193], v[110:113]
	v_mfma_f32_16x16x32_bf16 v[92:95], v[126:129], v[198:201], v[92:95]
	v_mfma_f32_16x16x32_bf16 v[88:91], v[142:145], v[198:201], v[88:91]
	v_mfma_f32_16x16x32_bf16 v[72:75], v[142:145], v[206:209], v[72:75]
	v_mfma_f32_16x16x32_bf16 v[76:79], v[126:129], v[206:209], v[76:79]
	v_mfma_f32_16x16x32_bf16 v[118:121], v[146:149], v[174:177], v[118:121]
	v_mfma_f32_16x16x32_bf16 v[114:117], v[154:157], v[174:177], v[114:117]
	v_mfma_f32_16x16x32_bf16 v[98:101], v[154:157], v[184:187], v[98:101]
	v_mfma_f32_16x16x32_bf16 v[102:105], v[146:149], v[184:187], v[102:105]
	v_mfma_f32_16x16x32_bf16 v[84:87], v[146:149], v[194:197], v[84:87]
	v_mfma_f32_16x16x32_bf16 v[80:83], v[154:157], v[194:197], v[80:83]
	v_mfma_f32_16x16x32_bf16 v[64:67], v[154:157], v[202:205], v[64:67]
	v_mfma_f32_16x16x32_bf16 v[68:71], v[146:149], v[202:205], v[68:71]
	v_mfma_f32_16x16x32_bf16 v[118:121], v[150:153], v[180:183], v[118:121]
	v_mfma_f32_16x16x32_bf16 v[114:117], v[170:173], v[180:183], v[114:117]
	v_mfma_f32_16x16x32_bf16 v[98:101], v[170:173], v[190:193], v[98:101]
	v_mfma_f32_16x16x32_bf16 v[102:105], v[150:153], v[190:193], v[102:105]
	v_mfma_f32_16x16x32_bf16 v[84:87], v[150:153], v[198:201], v[84:87]
	v_mfma_f32_16x16x32_bf16 v[80:83], v[170:173], v[198:201], v[80:83]
	v_mfma_f32_16x16x32_bf16 v[64:67], v[170:173], v[206:209], v[64:67]
	v_mfma_f32_16x16x32_bf16 v[68:71], v[150:153], v[206:209], v[68:71]
	s_barrier
	s_setprio 1
	s_add_i32 s18, s18, s96
	v_lshl_add_u64 v[178:179], s[2:3], 0, v[162:163]
	s_mov_b32 m0, s18
	ds_read_b128 v[174:177], v188 offset:16384
	ds_read_b128 v[180:183], v188 offset:17408
	ds_read_b128 v[184:187], v188 offset:18432
	ds_read_b128 v[190:193], v188 offset:19456
	ds_read_b128 v[194:197], v188 offset:20480
	ds_read_b128 v[198:201], v188 offset:21504
	ds_read_b128 v[202:205], v188 offset:22528
	ds_read_b128 v[206:209], v188 offset:23552
	global_load_lds_dwordx4 v162, s[2:3]
	s_add_i32 m0, s18, 0x2000
	v_lshl_add_u64 v[210:211], s[2:3], 0, v[158:159]
	s_add_u32 s2, s2, s48
	s_addc_u32 s3, s3, 0
	s_add_i32 s18, s38, s96
	global_load_lds_dwordx4 v[210:211], off
	v_lshl_add_u64 v[212:213], s[2:3], 0, v[162:163]
	s_mov_b32 m0, s18
	v_lshl_add_u64 v[214:215], s[2:3], 0, v[158:159]
	global_load_lds_dwordx4 v162, s[2:3]
	s_add_i32 m0, s18, 0x2000
	s_nop 0
	global_load_lds_dwordx4 v158, s[2:3]
	s_mov_b32 m0, s97
	s_nop 0
	global_load_lds_dwordx4 v164, s[42:43]
	s_mov_b32 m0, s22
	s_nop 0
	global_load_lds_dwordx4 v160, s[42:43]
	s_setprio 0
	s_waitcnt vmcnt(8)
	s_waitcnt lgkmcnt(0)
	s_barrier
	s_waitcnt lgkmcnt(0)
	v_mfma_f32_16x16x32_bf16 v[60:63], v[122:125], v[174:177], v[60:63]
	v_mfma_f32_16x16x32_bf16 v[56:59], v[138:141], v[174:177], v[56:59]
	v_mfma_f32_16x16x32_bf16 v[40:43], v[138:141], v[184:187], v[40:43]
	v_mfma_f32_16x16x32_bf16 v[44:47], v[122:125], v[184:187], v[44:47]
	v_mfma_f32_16x16x32_bf16 v[28:31], v[122:125], v[194:197], v[28:31]
	v_mfma_f32_16x16x32_bf16 v[24:27], v[138:141], v[194:197], v[24:27]
	v_mfma_f32_16x16x32_bf16 v[8:11], v[138:141], v[202:205], v[8:11]
	v_mfma_f32_16x16x32_bf16 v[12:15], v[122:125], v[202:205], v[12:15]
	v_mfma_f32_16x16x32_bf16 v[60:63], v[126:129], v[180:183], v[60:63]
	v_mfma_f32_16x16x32_bf16 v[56:59], v[142:145], v[180:183], v[56:59]
	v_mfma_f32_16x16x32_bf16 v[40:43], v[142:145], v[190:193], v[40:43]
	v_mfma_f32_16x16x32_bf16 v[44:47], v[126:129], v[190:193], v[44:47]
	v_mfma_f32_16x16x32_bf16 v[28:31], v[126:129], v[198:201], v[28:31]
	v_mfma_f32_16x16x32_bf16 v[24:27], v[142:145], v[198:201], v[24:27]
	v_mfma_f32_16x16x32_bf16 v[8:11], v[142:145], v[206:209], v[8:11]
	v_mfma_f32_16x16x32_bf16 v[12:15], v[126:129], v[206:209], v[12:15]
	v_mfma_f32_16x16x32_bf16 v[52:55], v[146:149], v[174:177], v[52:55]
	v_mfma_f32_16x16x32_bf16 v[48:51], v[154:157], v[174:177], v[48:51]
	v_mfma_f32_16x16x32_bf16 v[32:35], v[154:157], v[184:187], v[32:35]
	v_mfma_f32_16x16x32_bf16 v[36:39], v[146:149], v[184:187], v[36:39]
	v_mfma_f32_16x16x32_bf16 v[20:23], v[146:149], v[194:197], v[20:23]
	v_mfma_f32_16x16x32_bf16 v[16:19], v[154:157], v[194:197], v[16:19]
	v_mfma_f32_16x16x32_bf16 v[0:3], v[154:157], v[202:205], v[0:3]
	v_mfma_f32_16x16x32_bf16 v[4:7], v[146:149], v[202:205], v[4:7]
	v_mfma_f32_16x16x32_bf16 v[52:55], v[150:153], v[180:183], v[52:55]
	v_mfma_f32_16x16x32_bf16 v[48:51], v[170:173], v[180:183], v[48:51]
	v_mfma_f32_16x16x32_bf16 v[32:35], v[170:173], v[190:193], v[32:35]
	v_mfma_f32_16x16x32_bf16 v[36:39], v[150:153], v[190:193], v[36:39]
	v_mfma_f32_16x16x32_bf16 v[20:23], v[150:153], v[198:201], v[20:23]
	v_mfma_f32_16x16x32_bf16 v[16:19], v[170:173], v[198:201], v[16:19]
	v_mfma_f32_16x16x32_bf16 v[0:3], v[170:173], v[206:209], v[0:3]
	v_mfma_f32_16x16x32_bf16 v[4:7], v[150:153], v[206:209], v[4:7]
	s_barrier
	s_setprio 1
	s_add_i32 s18, 0, 0x18000
	s_add_i32 s38, 0, 0x1c000
	v_add_u32_e32 v142, s18, v97
	v_add_u32_e32 v170, s38, v97
	ds_read_b128 v[122:125], v142
	ds_read_b128 v[126:129], v142 offset:1024
	ds_read_b128 v[138:141], v142 offset:2048
	ds_read_b128 v[142:145], v142 offset:3072
	ds_read_b128 v[146:149], v170
	ds_read_b128 v[150:153], v170 offset:1024
	ds_read_b128 v[154:157], v170 offset:2048
	ds_read_b128 v[170:173], v170 offset:3072
	s_add_u32 s2, s42, s98
	s_addc_u32 s3, s43, 0
	s_mov_b32 m0, s23
	ds_read_b128 v[174:177], v188 offset:32768
	ds_read_b128 v[180:183], v188 offset:33792
	ds_read_b128 v[184:187], v188 offset:34816
	ds_read_b128 v[190:193], v188 offset:35840
	ds_read_b128 v[194:197], v188 offset:36864
	ds_read_b128 v[198:201], v188 offset:37888
	ds_read_b128 v[202:205], v188 offset:38912
	ds_read_b128 v[206:209], v188 offset:39936
	global_load_lds_dwordx4 v164, s[2:3]
	s_mov_b32 m0, s19
	s_nop 0
	global_load_lds_dwordx4 v160, s[2:3]
	s_setprio 0
	s_waitcnt vmcnt(8)
	s_waitcnt lgkmcnt(0)
	s_barrier
	s_waitcnt lgkmcnt(0)
	v_mfma_f32_16x16x32_bf16 v[134:137], v[122:125], v[174:177], v[134:137]
	v_mfma_f32_16x16x32_bf16 v[130:133], v[138:141], v[174:177], v[130:133]
	v_mfma_f32_16x16x32_bf16 v[106:109], v[138:141], v[184:187], v[106:109]
	v_mfma_f32_16x16x32_bf16 v[110:113], v[122:125], v[184:187], v[110:113]
	v_mfma_f32_16x16x32_bf16 v[92:95], v[122:125], v[194:197], v[92:95]
	v_mfma_f32_16x16x32_bf16 v[88:91], v[138:141], v[194:197], v[88:91]
	v_mfma_f32_16x16x32_bf16 v[72:75], v[138:141], v[202:205], v[72:75]
	v_mfma_f32_16x16x32_bf16 v[76:79], v[122:125], v[202:205], v[76:79]
	v_mfma_f32_16x16x32_bf16 v[134:137], v[126:129], v[180:183], v[134:137]
	v_mfma_f32_16x16x32_bf16 v[130:133], v[142:145], v[180:183], v[130:133]
	v_mfma_f32_16x16x32_bf16 v[106:109], v[142:145], v[190:193], v[106:109]
	v_mfma_f32_16x16x32_bf16 v[110:113], v[126:129], v[190:193], v[110:113]
	v_mfma_f32_16x16x32_bf16 v[92:95], v[126:129], v[198:201], v[92:95]
	v_mfma_f32_16x16x32_bf16 v[88:91], v[142:145], v[198:201], v[88:91]
	v_mfma_f32_16x16x32_bf16 v[72:75], v[142:145], v[206:209], v[72:75]
	v_mfma_f32_16x16x32_bf16 v[76:79], v[126:129], v[206:209], v[76:79]
	v_mfma_f32_16x16x32_bf16 v[118:121], v[146:149], v[174:177], v[118:121]
	v_mfma_f32_16x16x32_bf16 v[114:117], v[154:157], v[174:177], v[114:117]
	v_mfma_f32_16x16x32_bf16 v[98:101], v[154:157], v[184:187], v[98:101]
	v_mfma_f32_16x16x32_bf16 v[102:105], v[146:149], v[184:187], v[102:105]
	v_mfma_f32_16x16x32_bf16 v[84:87], v[146:149], v[194:197], v[84:87]
	v_mfma_f32_16x16x32_bf16 v[80:83], v[154:157], v[194:197], v[80:83]
	v_mfma_f32_16x16x32_bf16 v[64:67], v[154:157], v[202:205], v[64:67]
	v_mfma_f32_16x16x32_bf16 v[68:71], v[146:149], v[202:205], v[68:71]
	v_mfma_f32_16x16x32_bf16 v[118:121], v[150:153], v[180:183], v[118:121]
	v_mfma_f32_16x16x32_bf16 v[114:117], v[170:173], v[180:183], v[114:117]
	v_mfma_f32_16x16x32_bf16 v[98:101], v[170:173], v[190:193], v[98:101]
	v_mfma_f32_16x16x32_bf16 v[102:105], v[150:153], v[190:193], v[102:105]
	v_mfma_f32_16x16x32_bf16 v[84:87], v[150:153], v[198:201], v[84:87]
	v_mfma_f32_16x16x32_bf16 v[80:83], v[170:173], v[198:201], v[80:83]
	v_mfma_f32_16x16x32_bf16 v[64:67], v[170:173], v[206:209], v[64:67]
	v_mfma_f32_16x16x32_bf16 v[68:71], v[150:153], v[206:209], v[68:71]
	s_barrier
; template <class Epi, class Sched, bool ALIGN_EPI = false, bool SP2 = false>
; __device__ __forceinline__ void gemm_phase(PG8_LAS unsigned char* lds, const Gemm g, const Sched& S, const Epi& E) {
;     ...
;         for (int t = (Epi::PEEL ? 2 : 0); t < nt; t += 2) {
;             const bool last = (t == nt - 2);
;             const char* a1 = cA + (size_t)(t + 1) * kstepA;
;             const char* a2 = last ? nA : cA + (size_t)(t + 2) * kstepA; const char* b2 = last ? nB : cB + (size_t)(t + 2) * kstepB;
;             const char* a3 = a2 + kstepA; const char* b3 = b2 + kstepB;
;             PG8_ITER(8);
;         }
	s_setprio 1
	s_add_i32 s2, s18, s96
	v_lshl_add_u64 v[178:179], v[178:179], 0, s[36:37]
	s_mov_b32 m0, s2
	ds_read_b128 v[174:177], v188 offset:49152
	ds_read_b128 v[180:183], v188 offset:50176
	ds_read_b128 v[184:187], v188 offset:51200
	ds_read_b128 v[190:193], v188 offset:52224
	ds_read_b128 v[194:197], v188 offset:53248
	ds_read_b128 v[198:201], v188 offset:54272
	ds_read_b128 v[202:205], v188 offset:55296
	ds_read_b128 v[206:209], v188 offset:56320
	global_load_lds_dwordx4 v[178:179], off
	v_lshl_add_u64 v[178:179], v[210:211], 0, s[36:37]
	s_add_i32 m0, s2, 0x2000
	s_add_i32 s2, s38, s96
	global_load_lds_dwordx4 v[178:179], off
	v_lshl_add_u64 v[178:179], v[212:213], 0, s[36:37]
	s_mov_b32 m0, s2
	s_nop 0
	global_load_lds_dwordx4 v[178:179], off
	v_lshl_add_u64 v[178:179], v[214:215], 0, s[36:37]
	s_add_i32 m0, s2, 0x2000
	s_nop 0
	global_load_lds_dwordx4 v[178:179], off
	s_mov_b32 m0, s6
	s_nop 0
	global_load_lds_dwordx4 v164, s[44:45]
	s_mov_b32 m0, s56
	s_nop 0
	global_load_lds_dwordx4 v160, s[44:45]
	s_setprio 0
	s_waitcnt vmcnt(8)
	s_waitcnt lgkmcnt(0)
	s_barrier
	s_waitcnt lgkmcnt(0)
	v_mfma_f32_16x16x32_bf16 v[60:63], v[122:125], v[174:177], v[60:63]
	v_mfma_f32_16x16x32_bf16 v[56:59], v[138:141], v[174:177], v[56:59]
	v_mfma_f32_16x16x32_bf16 v[40:43], v[138:141], v[184:187], v[40:43]
	v_mfma_f32_16x16x32_bf16 v[44:47], v[122:125], v[184:187], v[44:47]
	v_mfma_f32_16x16x32_bf16 v[28:31], v[122:125], v[194:197], v[28:31]
	v_mfma_f32_16x16x32_bf16 v[24:27], v[138:141], v[194:197], v[24:27]
	v_mfma_f32_16x16x32_bf16 v[8:11], v[138:141], v[202:205], v[8:11]
	v_mfma_f32_16x16x32_bf16 v[12:15], v[122:125], v[202:205], v[12:15]
	v_mfma_f32_16x16x32_bf16 v[60:63], v[126:129], v[180:183], v[60:63]
	v_mfma_f32_16x16x32_bf16 v[56:59], v[142:145], v[180:183], v[56:59]
	v_mfma_f32_16x16x32_bf16 v[40:43], v[142:145], v[190:193], v[40:43]
	v_mfma_f32_16x16x32_bf16 v[44:47], v[126:129], v[190:193], v[44:47]
	v_mfma_f32_16x16x32_bf16 v[28:31], v[126:129], v[198:201], v[28:31]
	v_mfma_f32_16x16x32_bf16 v[24:27], v[142:145], v[198:201], v[24:27]
	v_mfma_f32_16x16x32_bf16 v[8:11], v[142:145], v[206:209], v[8:11]
	v_mfma_f32_16x16x32_bf16 v[12:15], v[126:129], v[206:209], v[12:15]
	v_mfma_f32_16x16x32_bf16 v[52:55], v[146:149], v[174:177], v[52:55]
	v_mfma_f32_16x16x32_bf16 v[48:51], v[154:157], v[174:177], v[48:51]
	v_mfma_f32_16x16x32_bf16 v[32:35], v[154:157], v[184:187], v[32:35]
	v_mfma_f32_16x16x32_bf16 v[36:39], v[146:149], v[184:187], v[36:39]
	v_mfma_f32_16x16x32_bf16 v[20:23], v[146:149], v[194:197], v[20:23]
	v_mfma_f32_16x16x32_bf16 v[16:19], v[154:157], v[194:197], v[16:19]
	v_mfma_f32_16x16x32_bf16 v[0:3], v[154:157], v[202:205], v[0:3]
	v_mfma_f32_16x16x32_bf16 v[4:7], v[146:149], v[202:205], v[4:7]
	v_mfma_f32_16x16x32_bf16 v[52:55], v[150:153], v[180:183], v[52:55]
	v_mfma_f32_16x16x32_bf16 v[48:51], v[170:173], v[180:183], v[48:51]
	v_mfma_f32_16x16x32_bf16 v[32:35], v[170:173], v[190:193], v[32:35]
	v_mfma_f32_16x16x32_bf16 v[36:39], v[150:153], v[190:193], v[36:39]
	v_mfma_f32_16x16x32_bf16 v[20:23], v[150:153], v[198:201], v[20:23]
	v_mfma_f32_16x16x32_bf16 v[16:19], v[170:173], v[198:201], v[16:19]
	v_mfma_f32_16x16x32_bf16 v[0:3], v[170:173], v[206:209], v[0:3]
	v_mfma_f32_16x16x32_bf16 v[4:7], v[150:153], v[206:209], v[4:7]
	s_barrier
	s_setprio 1
	s_add_u32 s58, s58, 0x100
	s_addc_u32 s59, s59, 0
	s_add_u32 s24, s24, s49
	s_addc_u32 s25, s25, 0
	s_cmp_ge_u32 s10, s8
	s_cbranch_scc1 .LBB0_348

; #define PG8_WAIT_V(n) asm volatile("s_waitcnt vmcnt(" #n ")" ::: "memory")
; #define PG8_BAR __builtin_amdgcn_s_barrier()
; template <class Epi, class Sched, bool ALIGN_EPI = false, bool SP2 = false>
; __device__ __forceinline__ void gemm_phase(PG8_LAS unsigned char* lds, const Gemm g, const Sched& S, const Epi& E) {
;     ...
;     PG8_WAIT_V(0);
;     if constexpr (!ALIGN_EPI) { if (wr == 0) PG8_BAR; }
;     PG8_BAR;
.LBB0_449:
	s_setprio 0
	s_waitcnt vmcnt(0)
	v_readlane_b32 s52, v254, 58
	v_readlane_b32 s38, v255, 19
	v_readlane_b32 s50, v254, 56
	v_readlane_b32 s53, v254, 59
	v_readlane_b32 s56, v254, 60
	v_readlane_b32 s54, v255, 23
	v_readlane_b32 s39, v255, 20
	v_readlane_b32 s19, v254, 48
	v_readlane_b32 s22, v254, 49
	v_readlane_b32 s23, v254, 50
	v_readlane_b32 s44, v254, 51
	v_readlane_b32 s45, v254, 52
	v_readlane_b32 s46, v254, 53
	v_readlane_b32 s47, v254, 54
	v_readlane_b32 s48, v254, 55
	v_readlane_b32 s51, v254, 57
	v_readlane_b32 s57, v254, 61
	v_readlane_b32 s49, v254, 62
	s_mov_b32 s53, 0x409b43d5
	v_readlane_b32 s31, v255, 17
	v_readlane_b32 s55, v255, 24
	s_barrier

; template <class Epi, class Sched, bool ALIGN_EPI = false, bool SP2 = false>
; __device__ __forceinline__ void gemm_phase(PG8_LAS unsigned char* lds, const Gemm g, const Sched& S, const Epi& E) {
;     ...
;         const bool has_next = S.next(ui + 1, nxt);
;         const char* nA = has_next ? (const char*)g.A + (size_t)nxt.pm * tstepA : cA; const char* nB = has_next ? (const char*)g.Bt + (size_t)nxt.pn * tstepB : cB;
;     ...
;         if constexpr (Epi::PEEL) {
;             const char* a1 = cA + kstepA; const char* a2 = cA + 2 * kstepA; const char* b2 = cB + 2 * kstepB; const char* a3 = a2 + kstepA; const char* b3 = b2 + kstepB;
;             PG8_ITER(8);
.LBB0_477:
	s_ashr_i32 s27, s26, 31
	s_lshl_b64 s[2:3], s[26:27], 15
	v_readlane_b32 s10, v255, 15
	s_add_u32 s28, s10, s2
	v_readlane_b32 s2, v255, 16
	s_addc_u32 s29, s2, s3
	s_ashr_i32 s25, s24, 31
	s_lshl_b64 s[2:3], s[24:25], 19
	s_add_u32 s30, s19, s2
	s_addc_u32 s31, s22, s3
	s_add_u32 s44, s34, 0x800000
	s_addc_u32 s45, s35, 0
	s_add_u32 s42, s34, 0xc00000
	s_addc_u32 s43, s35, 0
	s_add_i32 s61, 0, 0x10000
	s_and_b64 s[2:3], s[40:41], exec
	s_cselect_b32 s25, s29, s35
	s_cselect_b32 s27, s28, s34
	s_add_i32 s97, 0, 0x14000
	v_add_u32_e32 v142, s61, v97
	v_add_u32_e32 v143, s97, v97
	ds_read_b128 v[0:3], v142
	ds_read_b128 v[4:7], v142 offset:1024
	ds_read_b128 v[8:11], v142 offset:2048
	ds_read_b128 v[12:15], v142 offset:3072
	ds_read_b128 v[16:19], v143
	s_waitcnt lgkmcnt(0)
	ds_read_b128 v[20:23], v143 offset:1024
	ds_read_b128 v[24:27], v143 offset:2048
	ds_read_b128 v[28:31], v143 offset:3072
	s_and_b64 s[2:3], s[40:41], exec
	s_cselect_b32 s57, s31, s1
	s_cselect_b32 s58, s30, s0
	s_add_u32 s2, s34, 0x404000
	s_addc_u32 s3, s35, 0
	s_add_i32 s59, s23, 0xc000
	s_mov_b32 m0, s59
	s_add_i32 s60, s23, 0xe000
	ds_read_b128 v[32:35], v156
	ds_read_b128 v[36:39], v156 offset:1024
	ds_read_b128 v[40:43], v156 offset:2048
	ds_read_b128 v[44:47], v156 offset:3072
	ds_read_b128 v[48:51], v156 offset:4096
	ds_read_b128 v[52:55], v156 offset:5120
	ds_read_b128 v[56:59], v156 offset:6144
	ds_read_b128 v[60:63], v156 offset:7168
	global_load_lds_dwordx4 v130, s[2:3]
	s_mov_b32 m0, s60
	s_nop 0
	global_load_lds_dwordx4 v134, s[2:3]
	s_setprio 0
	s_waitcnt vmcnt(8)
	s_waitcnt lgkmcnt(0)
	s_barrier
	s_waitcnt lgkmcnt(0)
	v_mfma_f32_16x16x32_bf16 v[88:91], v[0:3], v[56:59], 0
	v_mfma_f32_16x16x32_bf16 v[64:67], v[0:3], v[32:35], 0
	v_mfma_f32_16x16x32_bf16 v[68:71], v[8:11], v[32:35], 0
	v_mfma_f32_16x16x32_bf16 v[72:75], v[0:3], v[40:43], 0
	v_mfma_f32_16x16x32_bf16 v[76:79], v[8:11], v[40:43], 0
	v_mfma_f32_16x16x32_bf16 v[80:83], v[0:3], v[48:51], 0
	v_mfma_f32_16x16x32_bf16 v[84:87], v[8:11], v[48:51], 0
	v_mfma_f32_16x16x32_bf16 v[92:95], v[4:7], v[60:63], v[88:91]
	v_mfma_f32_16x16x32_bf16 v[88:91], v[8:11], v[56:59], 0
	v_mfma_f32_16x16x32_bf16 v[64:67], v[4:7], v[36:39], v[64:67]
	v_mfma_f32_16x16x32_bf16 v[68:71], v[12:15], v[36:39], v[68:71]
	v_mfma_f32_16x16x32_bf16 v[72:75], v[4:7], v[44:47], v[72:75]
	v_mfma_f32_16x16x32_bf16 v[76:79], v[12:15], v[44:47], v[76:79]
	v_mfma_f32_16x16x32_bf16 v[80:83], v[4:7], v[52:55], v[80:83]
	v_mfma_f32_16x16x32_bf16 v[84:87], v[12:15], v[52:55], v[84:87]
	v_mfma_f32_16x16x32_bf16 v[102:105], v[12:15], v[60:63], v[88:91]
	v_mfma_f32_16x16x32_bf16 v[88:91], v[16:19], v[32:35], 0
	v_mfma_f32_16x16x32_bf16 v[32:35], v[24:27], v[32:35], 0
	v_mfma_f32_16x16x32_bf16 v[110:113], v[20:23], v[36:39], v[88:91]
	v_mfma_f32_16x16x32_bf16 v[32:35], v[28:31], v[36:39], v[32:35]
	v_mfma_f32_16x16x32_bf16 v[36:39], v[16:19], v[40:43], 0
	v_mfma_f32_16x16x32_bf16 v[40:43], v[24:27], v[40:43], 0
	v_mfma_f32_16x16x32_bf16 v[36:39], v[20:23], v[44:47], v[36:39]
	v_mfma_f32_16x16x32_bf16 v[40:43], v[28:31], v[44:47], v[40:43]
	v_mfma_f32_16x16x32_bf16 v[44:47], v[16:19], v[48:51], 0
	v_mfma_f32_16x16x32_bf16 v[48:51], v[24:27], v[48:51], 0
	v_mfma_f32_16x16x32_bf16 v[44:47], v[20:23], v[52:55], v[44:47]
	v_mfma_f32_16x16x32_bf16 v[48:51], v[28:31], v[52:55], v[48:51]
	v_mfma_f32_16x16x32_bf16 v[52:55], v[16:19], v[56:59], 0
	v_mfma_f32_16x16x32_bf16 v[56:59], v[24:27], v[56:59], 0
	v_mfma_f32_16x16x32_bf16 v[52:55], v[20:23], v[60:63], v[52:55]
	v_mfma_f32_16x16x32_bf16 v[56:59], v[28:31], v[60:63], v[56:59]
	s_barrier
	s_setprio 1
	v_lshl_add_u64 v[154:155], s[0:1], 0, v[132:133]
	s_mov_b64 s[2:3], 0x100
	s_add_i32 s61, s61, s9
	v_lshl_add_u64 v[144:145], v[154:155], 0, s[2:3]
	s_mov_b32 m0, s61
	v_lshl_add_u64 v[178:179], s[0:1], 0, v[136:137]
	s_add_i32 s96, s61, 0x2000
	ds_read_b128 v[60:63], v156 offset:16384
	ds_read_b128 v[88:91], v156 offset:17408
	ds_read_b128 v[98:101], v156 offset:18432
	ds_read_b128 v[106:109], v156 offset:19456
	ds_read_b128 v[114:117], v156 offset:20480
	ds_read_b128 v[118:121], v156 offset:21504
	ds_read_b128 v[122:125], v156 offset:22528
	ds_read_b128 v[126:129], v156 offset:23552
	global_load_lds_dwordx4 v[144:145], off
	v_lshl_add_u64 v[144:145], v[178:179], 0, s[2:3]
	s_add_u32 s2, s0, 0x40100
	s_mov_b32 m0, s96
	s_addc_u32 s3, s1, 0
	s_add_i32 s97, s97, s9
	global_load_lds_dwordx4 v[144:145], off
	s_mov_b32 m0, s97
	s_add_i32 s98, s97, 0x2000
	global_load_lds_dwordx4 v132, s[2:3]
	s_mov_b32 m0, s98
	s_nop 0
	global_load_lds_dwordx4 v136, s[2:3]
	s_mov_b32 m0, s23
	s_nop 0
	global_load_lds_dwordx4 v130, s[44:45]
	s_mov_b32 m0, s39
	s_nop 0
	global_load_lds_dwordx4 v134, s[44:45]
	s_setprio 0
	s_waitcnt vmcnt(8)
	s_waitcnt lgkmcnt(0)
	s_barrier
	s_waitcnt lgkmcnt(0)
	v_mfma_f32_16x16x32_bf16 v[144:147], v[0:3], v[60:63], 0
	v_mfma_f32_16x16x32_bf16 v[158:161], v[0:3], v[98:101], 0
	v_mfma_f32_16x16x32_bf16 v[166:169], v[0:3], v[114:117], 0
	v_mfma_f32_16x16x32_bf16 v[0:3], v[0:3], v[122:125], 0
	v_mfma_f32_16x16x32_bf16 v[146:149], v[4:7], v[88:91], v[144:147]
	v_mfma_f32_16x16x32_bf16 v[158:161], v[4:7], v[106:109], v[158:161]
	v_mfma_f32_16x16x32_bf16 v[166:169], v[4:7], v[118:121], v[166:169]
	v_mfma_f32_16x16x32_bf16 v[0:3], v[4:7], v[126:129], v[0:3]
	v_mfma_f32_16x16x32_bf16 v[4:7], v[8:11], v[122:125], 0
	v_mfma_f32_16x16x32_bf16 v[150:153], v[8:11], v[60:63], 0
	v_mfma_f32_16x16x32_bf16 v[162:165], v[8:11], v[98:101], 0
	v_mfma_f32_16x16x32_bf16 v[170:173], v[8:11], v[114:117], 0
	v_mfma_f32_16x16x32_bf16 v[4:7], v[12:15], v[126:129], v[4:7]
	v_mfma_f32_16x16x32_bf16 v[150:153], v[12:15], v[88:91], v[150:153]
	v_mfma_f32_16x16x32_bf16 v[162:165], v[12:15], v[106:109], v[162:165]
	v_mfma_f32_16x16x32_bf16 v[170:173], v[12:15], v[118:121], v[170:173]
	v_mfma_f32_16x16x32_bf16 v[8:11], v[16:19], v[60:63], 0
	v_mfma_f32_16x16x32_bf16 v[12:15], v[20:23], v[88:91], v[8:11]
	v_mfma_f32_16x16x32_bf16 v[8:11], v[24:27], v[60:63], 0
	v_mfma_f32_16x16x32_bf16 v[174:177], v[28:31], v[88:91], v[8:11]
	v_mfma_f32_16x16x32_bf16 v[8:11], v[16:19], v[98:101], 0
	v_mfma_f32_16x16x32_bf16 v[188:191], v[20:23], v[106:109], v[8:11]
	v_mfma_f32_16x16x32_bf16 v[8:11], v[24:27], v[98:101], 0
	v_mfma_f32_16x16x32_bf16 v[192:195], v[28:31], v[106:109], v[8:11]
	v_mfma_f32_16x16x32_bf16 v[8:11], v[16:19], v[114:117], 0
	v_mfma_f32_16x16x32_bf16 v[196:199], v[20:23], v[118:121], v[8:11]
	v_mfma_f32_16x16x32_bf16 v[8:11], v[24:27], v[114:117], 0
	v_mfma_f32_16x16x32_bf16 v[200:203], v[28:31], v[118:121], v[8:11]
	v_mfma_f32_16x16x32_bf16 v[8:11], v[16:19], v[122:125], 0
	v_mfma_f32_16x16x32_bf16 v[204:207], v[20:23], v[126:129], v[8:11]
	v_mfma_f32_16x16x32_bf16 v[8:11], v[24:27], v[122:125], 0
	v_mfma_f32_16x16x32_bf16 v[208:211], v[28:31], v[126:129], v[8:11]
	s_barrier
	s_setprio 1
	s_add_i32 s99, 0, 0x18000
	s_add_i32 vcc_hi, 0, 0x1c000
	v_add_u32_e32 v144, s99, v97
	v_add_u32_e32 v145, vcc_hi, v97
	s_nop 0
	ds_read_b128 v[8:11], v144
	ds_read_b128 v[20:23], v144 offset:1024
	ds_read_b128 v[28:31], v144 offset:2048
	ds_read_b128 v[212:215], v144 offset:3072
	ds_read_b128 v[216:219], v145
	ds_read_b128 v[220:223], v145 offset:1024
	ds_read_b128 v[234:237], v145 offset:2048
	ds_read_b128 v[238:241], v145 offset:3072
	s_add_u32 s2, s34, 0x804000
	s_addc_u32 s3, s35, 0
	s_mov_b32 m0, s46
	ds_read_b128 v[16:19], v156 offset:32768
	ds_read_b128 v[24:27], v156 offset:33792
	ds_read_b128 v[242:245], v156 offset:34816
	ds_read_b128 v[246:249], v156 offset:35840
	ds_read_b128 v[228:231], v156 offset:36864
	ds_read_b128 v[180:183], v156 offset:37888
	ds_read_b128 v[184:187], v156 offset:38912
	ds_read_b128 v[224:227], v156 offset:39936
	global_load_lds_dwordx4 v130, s[2:3]
	s_mov_b32 m0, s47
	s_nop 0
	global_load_lds_dwordx4 v134, s[2:3]
	s_setprio 0
	s_waitcnt vmcnt(8)
	s_waitcnt lgkmcnt(0)
	s_barrier
	s_waitcnt lgkmcnt(0)
	v_mfma_f32_16x16x32_bf16 v[60:63], v[8:11], v[16:19], v[64:67]
	v_mfma_f32_16x16x32_bf16 v[122:125], v[20:23], v[24:27], v[60:63]
	v_mfma_f32_16x16x32_bf16 v[60:63], v[28:31], v[16:19], v[68:71]
	v_mfma_f32_16x16x32_bf16 v[114:117], v[212:215], v[24:27], v[60:63]
	v_mfma_f32_16x16x32_bf16 v[60:63], v[8:11], v[242:245], v[72:75]
	v_mfma_f32_16x16x32_bf16 v[106:109], v[20:23], v[246:249], v[60:63]
	v_mfma_f32_16x16x32_bf16 v[60:63], v[28:31], v[242:245], v[76:79]
	v_mfma_f32_16x16x32_bf16 v[98:101], v[212:215], v[246:249], v[60:63]
	v_mfma_f32_16x16x32_bf16 v[60:63], v[8:11], v[228:231], v[80:83]
	v_mfma_f32_16x16x32_bf16 v[88:91], v[20:23], v[180:183], v[60:63]
	v_mfma_f32_16x16x32_bf16 v[60:63], v[28:31], v[228:231], v[84:87]
	v_mfma_f32_16x16x32_bf16 v[80:83], v[212:215], v[180:183], v[60:63]
	v_mfma_f32_16x16x32_bf16 v[60:63], v[8:11], v[184:187], v[92:95]
	v_mfma_f32_16x16x32_bf16 v[72:75], v[20:23], v[224:227], v[60:63]
	v_mfma_f32_16x16x32_bf16 v[60:63], v[28:31], v[184:187], v[102:105]
	v_mfma_f32_16x16x32_bf16 v[60:63], v[212:215], v[224:227], v[60:63]
	v_mfma_f32_16x16x32_bf16 v[64:67], v[216:219], v[16:19], v[110:113]
	v_mfma_f32_16x16x32_bf16 v[16:19], v[234:237], v[16:19], v[32:35]
	v_mfma_f32_16x16x32_bf16 v[118:121], v[238:241], v[24:27], v[16:19]
	v_mfma_f32_16x16x32_bf16 v[16:19], v[216:219], v[242:245], v[36:39]
	v_mfma_f32_16x16x32_bf16 v[110:113], v[220:223], v[246:249], v[16:19]
	v_mfma_f32_16x16x32_bf16 v[16:19], v[234:237], v[242:245], v[40:43]
	v_mfma_f32_16x16x32_bf16 v[102:105], v[238:241], v[246:249], v[16:19]
	v_mfma_f32_16x16x32_bf16 v[16:19], v[216:219], v[228:231], v[44:47]
	v_mfma_f32_16x16x32_bf16 v[92:95], v[220:223], v[180:183], v[16:19]
	v_mfma_f32_16x16x32_bf16 v[16:19], v[234:237], v[228:231], v[48:51]
	v_mfma_f32_16x16x32_bf16 v[84:87], v[238:241], v[180:183], v[16:19]
	v_mfma_f32_16x16x32_bf16 v[16:19], v[216:219], v[184:187], v[52:55]
	v_mfma_f32_16x16x32_bf16 v[76:79], v[220:223], v[224:227], v[16:19]
	v_mfma_f32_16x16x32_bf16 v[16:19], v[234:237], v[184:187], v[56:59]
	v_mfma_f32_16x16x32_bf16 v[126:129], v[220:223], v[24:27], v[64:67]
	v_mfma_f32_16x16x32_bf16 v[68:71], v[238:241], v[224:227], v[16:19]
	s_barrier
; template <class Epi, class Sched, bool ALIGN_EPI = false, bool SP2 = false>
; __device__ __forceinline__ void gemm_phase(PG8_LAS unsigned char* lds, const Gemm g, const Sched& S, const Epi& E) {
;     ...
;             const bool last = (t == nt - 2);
;             const char* a1 = cA + (size_t)(t + 1) * kstepA;
;             const char* a2 = last ? nA : cA + (size_t)(t + 2) * kstepA; const char* b2 = last ? nB : cB + (size_t)(t + 2) * kstepB;
	s_setprio 1
	s_mov_b64 s[2:3], 0x180
	s_add_i32 s99, s99, s9
	s_nop 1
	v_lshl_add_u64 v[16:17], v[154:155], 0, s[2:3]
	s_mov_b32 m0, s99
	s_add_i32 vcc_lo, s99, 0x2000
	ds_read_b128 v[36:39], v156 offset:49152
	ds_read_b128 v[44:47], v156 offset:50176
	ds_read_b128 v[180:183], v156 offset:51200
	ds_read_b128 v[184:187], v156 offset:52224
	ds_read_b128 v[224:227], v156 offset:53248
	ds_read_b128 v[228:231], v156 offset:54272
	ds_read_b128 v[242:245], v156 offset:55296
	ds_read_b128 v[246:249], v156 offset:56320
	global_load_lds_dwordx4 v[16:17], off
	v_lshl_add_u64 v[16:17], v[178:179], 0, s[2:3]
	s_add_u32 s2, s0, 0x40180
	s_mov_b32 m0, vcc_lo
	s_addc_u32 s3, s1, 0
	s_add_i32 vcc_hi, vcc_hi, s9
	global_load_lds_dwordx4 v[16:17], off
	s_mov_b32 m0, vcc_hi
	s_add_i32 s38, vcc_hi, 0x2000
	global_load_lds_dwordx4 v132, s[2:3]
	s_mov_b32 m0, s38
	s_nop 0
	global_load_lds_dwordx4 v136, s[2:3]
	s_mov_b32 m0, s49
	s_nop 0
	global_load_lds_dwordx4 v130, s[42:43]
	s_mov_b32 m0, s50
	s_nop 0
	global_load_lds_dwordx4 v134, s[42:43]
	s_setprio 0
	s_waitcnt vmcnt(8)
	s_waitcnt lgkmcnt(0)
	s_barrier
	s_waitcnt lgkmcnt(0)
	v_mfma_f32_16x16x32_bf16 v[16:19], v[8:11], v[36:39], v[146:149]
	v_mfma_f32_16x16x32_bf16 v[56:59], v[20:23], v[44:47], v[16:19]
	v_mfma_f32_16x16x32_bf16 v[16:19], v[28:31], v[36:39], v[150:153]
	v_mfma_f32_16x16x32_bf16 v[48:51], v[212:215], v[44:47], v[16:19]
	v_mfma_f32_16x16x32_bf16 v[16:19], v[8:11], v[180:183], v[158:161]
	v_mfma_f32_16x16x32_bf16 v[40:43], v[20:23], v[184:187], v[16:19]
	v_mfma_f32_16x16x32_bf16 v[16:19], v[28:31], v[180:183], v[162:165]
	v_mfma_f32_16x16x32_bf16 v[32:35], v[212:215], v[184:187], v[16:19]
	v_mfma_f32_16x16x32_bf16 v[16:19], v[8:11], v[224:227], v[166:169]
	v_mfma_f32_16x16x32_bf16 v[0:3], v[8:11], v[242:245], v[0:3]
	v_mfma_f32_16x16x32_bf16 v[24:27], v[20:23], v[228:231], v[16:19]
	v_mfma_f32_16x16x32_bf16 v[16:19], v[28:31], v[224:227], v[170:173]
	v_mfma_f32_16x16x32_bf16 v[8:11], v[20:23], v[246:249], v[0:3]
	v_mfma_f32_16x16x32_bf16 v[0:3], v[28:31], v[242:245], v[4:7]
	v_mfma_f32_16x16x32_bf16 v[16:19], v[212:215], v[228:231], v[16:19]
	v_mfma_f32_16x16x32_bf16 v[0:3], v[212:215], v[246:249], v[0:3]
	v_mfma_f32_16x16x32_bf16 v[4:7], v[216:219], v[36:39], v[12:15]
	v_mfma_f32_16x16x32_bf16 v[64:67], v[220:223], v[44:47], v[4:7]
	v_mfma_f32_16x16x32_bf16 v[4:7], v[234:237], v[36:39], v[174:177]
	v_mfma_f32_16x16x32_bf16 v[52:55], v[238:241], v[44:47], v[4:7]
	v_mfma_f32_16x16x32_bf16 v[4:7], v[216:219], v[180:183], v[188:191]
	v_mfma_f32_16x16x32_bf16 v[44:47], v[220:223], v[184:187], v[4:7]
	v_mfma_f32_16x16x32_bf16 v[4:7], v[234:237], v[180:183], v[192:195]
	v_mfma_f32_16x16x32_bf16 v[36:39], v[238:241], v[184:187], v[4:7]
	v_mfma_f32_16x16x32_bf16 v[4:7], v[216:219], v[224:227], v[196:199]
	v_mfma_f32_16x16x32_bf16 v[28:31], v[220:223], v[228:231], v[4:7]
	v_mfma_f32_16x16x32_bf16 v[4:7], v[234:237], v[224:227], v[200:203]
	v_mfma_f32_16x16x32_bf16 v[20:23], v[238:241], v[228:231], v[4:7]
	v_mfma_f32_16x16x32_bf16 v[4:7], v[216:219], v[242:245], v[204:207]
	v_mfma_f32_16x16x32_bf16 v[12:15], v[220:223], v[246:249], v[4:7]
	v_mfma_f32_16x16x32_bf16 v[4:7], v[234:237], v[242:245], v[208:211]
	v_mfma_f32_16x16x32_bf16 v[4:7], v[238:241], v[246:249], v[4:7]
	s_barrier
	s_setprio 1
	s_add_u32 s3, s0, 0x200
	s_addc_u32 s2, s1, 0
	s_add_u32 s0, s34, 0xc04000
	s_addc_u32 s1, s35, 0
	s_mov_b32 s18, 0
.LBB0_478:
	ds_read_b128 v[146:149], v142
	ds_read_b128 v[150:153], v142 offset:1024
	ds_read_b128 v[158:161], v142 offset:2048
	ds_read_b128 v[162:165], v142 offset:3072
	ds_read_b128 v[166:169], v143
	ds_read_b128 v[170:173], v143 offset:1024
	ds_read_b128 v[174:177], v143 offset:2048
	ds_read_b128 v[180:183], v143 offset:3072
	s_add_u32 s10, s0, 0x3fc000
	s_addc_u32 s11, s1, 0
	s_cmp_eq_u32 s18, 12
	s_cselect_b32 s44, s27, s10
	s_cselect_b32 s45, s25, s11
	s_cselect_b32 s42, s58, s3
	s_cselect_b32 s43, s57, s2
	s_add_u32 s34, s44, 0x400000
	s_addc_u32 s35, s45, 0
	s_mov_b32 m0, s59
	ds_read_b128 v[184:187], v156
	ds_read_b128 v[188:191], v156 offset:1024
	ds_read_b128 v[192:195], v156 offset:2048
	ds_read_b128 v[196:199], v156 offset:3072
	ds_read_b128 v[200:203], v156 offset:4096
	ds_read_b128 v[204:207], v156 offset:5120
	ds_read_b128 v[208:211], v156 offset:6144
	ds_read_b128 v[212:215], v156 offset:7168
	global_load_lds_dwordx4 v140, s[0:1]
	s_mov_b32 m0, s60
	s_nop 0
	global_load_lds_dwordx4 v138, s[0:1]
	s_setprio 0
	s_waitcnt vmcnt(8)
	s_waitcnt lgkmcnt(0)
	s_barrier
	s_waitcnt lgkmcnt(0)
	v_mfma_f32_16x16x32_bf16 v[122:125], v[146:149], v[184:187], v[122:125]
	v_mfma_f32_16x16x32_bf16 v[114:117], v[158:161], v[184:187], v[114:117]
	v_mfma_f32_16x16x32_bf16 v[98:101], v[158:161], v[192:195], v[98:101]
	v_mfma_f32_16x16x32_bf16 v[106:109], v[146:149], v[192:195], v[106:109]
	v_mfma_f32_16x16x32_bf16 v[88:91], v[146:149], v[200:203], v[88:91]
	v_mfma_f32_16x16x32_bf16 v[80:83], v[158:161], v[200:203], v[80:83]
	v_mfma_f32_16x16x32_bf16 v[60:63], v[158:161], v[208:211], v[60:63]
	v_mfma_f32_16x16x32_bf16 v[72:75], v[146:149], v[208:211], v[72:75]
	v_mfma_f32_16x16x32_bf16 v[122:125], v[150:153], v[188:191], v[122:125]
	v_mfma_f32_16x16x32_bf16 v[114:117], v[162:165], v[188:191], v[114:117]
	v_mfma_f32_16x16x32_bf16 v[98:101], v[162:165], v[196:199], v[98:101]
	v_mfma_f32_16x16x32_bf16 v[106:109], v[150:153], v[196:199], v[106:109]
	v_mfma_f32_16x16x32_bf16 v[88:91], v[150:153], v[204:207], v[88:91]
	v_mfma_f32_16x16x32_bf16 v[80:83], v[162:165], v[204:207], v[80:83]
	v_mfma_f32_16x16x32_bf16 v[60:63], v[162:165], v[212:215], v[60:63]
	v_mfma_f32_16x16x32_bf16 v[72:75], v[150:153], v[212:215], v[72:75]
	v_mfma_f32_16x16x32_bf16 v[126:129], v[166:169], v[184:187], v[126:129]
	v_mfma_f32_16x16x32_bf16 v[118:121], v[174:177], v[184:187], v[118:121]
	v_mfma_f32_16x16x32_bf16 v[102:105], v[174:177], v[192:195], v[102:105]
	v_mfma_f32_16x16x32_bf16 v[110:113], v[166:169], v[192:195], v[110:113]
	v_mfma_f32_16x16x32_bf16 v[92:95], v[166:169], v[200:203], v[92:95]
	v_mfma_f32_16x16x32_bf16 v[84:87], v[174:177], v[200:203], v[84:87]
	v_mfma_f32_16x16x32_bf16 v[68:71], v[174:177], v[208:211], v[68:71]
	v_mfma_f32_16x16x32_bf16 v[76:79], v[166:169], v[208:211], v[76:79]
	v_mfma_f32_16x16x32_bf16 v[126:129], v[170:173], v[188:191], v[126:129]
	v_mfma_f32_16x16x32_bf16 v[118:121], v[180:183], v[188:191], v[118:121]
	v_mfma_f32_16x16x32_bf16 v[102:105], v[180:183], v[196:199], v[102:105]
	v_mfma_f32_16x16x32_bf16 v[110:113], v[170:173], v[196:199], v[110:113]
	v_mfma_f32_16x16x32_bf16 v[92:95], v[170:173], v[204:207], v[92:95]
	v_mfma_f32_16x16x32_bf16 v[84:87], v[180:183], v[204:207], v[84:87]
	v_mfma_f32_16x16x32_bf16 v[68:71], v[180:183], v[212:215], v[68:71]
	v_mfma_f32_16x16x32_bf16 v[76:79], v[170:173], v[212:215], v[76:79]
	s_barrier
	s_setprio 1
	s_mov_b32 m0, s61
	s_add_u32 s10, s42, 0x40000
	ds_read_b128 v[184:187], v156 offset:16384
	ds_read_b128 v[188:191], v156 offset:17408
	ds_read_b128 v[192:195], v156 offset:18432
	ds_read_b128 v[196:199], v156 offset:19456
	ds_read_b128 v[200:203], v156 offset:20480
	ds_read_b128 v[204:207], v156 offset:21504
	ds_read_b128 v[208:211], v156 offset:22528
	ds_read_b128 v[212:215], v156 offset:23552
	global_load_lds_dwordx4 v132, s[42:43]
	s_mov_b32 m0, s96
	s_addc_u32 s11, s43, 0
	global_load_lds_dwordx4 v136, s[42:43]
	s_mov_b32 m0, s97
	s_nop 0
	global_load_lds_dwordx4 v132, s[10:11]
	s_mov_b32 m0, s98
	s_nop 0
	global_load_lds_dwordx4 v136, s[10:11]
	s_mov_b32 m0, s23
	s_nop 0
	global_load_lds_dwordx4 v130, s[44:45]
	s_mov_b32 m0, s39
	s_nop 0
	global_load_lds_dwordx4 v134, s[44:45]
	s_setprio 0
	s_waitcnt vmcnt(8)
	s_waitcnt lgkmcnt(0)
	s_barrier
	s_waitcnt lgkmcnt(0)
	v_mfma_f32_16x16x32_bf16 v[56:59], v[146:149], v[184:187], v[56:59]
	v_mfma_f32_16x16x32_bf16 v[48:51], v[158:161], v[184:187], v[48:51]
	v_mfma_f32_16x16x32_bf16 v[32:35], v[158:161], v[192:195], v[32:35]
	v_mfma_f32_16x16x32_bf16 v[40:43], v[146:149], v[192:195], v[40:43]
	v_mfma_f32_16x16x32_bf16 v[24:27], v[146:149], v[200:203], v[24:27]
	v_mfma_f32_16x16x32_bf16 v[16:19], v[158:161], v[200:203], v[16:19]
	v_mfma_f32_16x16x32_bf16 v[0:3], v[158:161], v[208:211], v[0:3]
	v_mfma_f32_16x16x32_bf16 v[8:11], v[146:149], v[208:211], v[8:11]
	v_mfma_f32_16x16x32_bf16 v[56:59], v[150:153], v[188:191], v[56:59]
	v_mfma_f32_16x16x32_bf16 v[48:51], v[162:165], v[188:191], v[48:51]
	v_mfma_f32_16x16x32_bf16 v[32:35], v[162:165], v[196:199], v[32:35]
	v_mfma_f32_16x16x32_bf16 v[40:43], v[150:153], v[196:199], v[40:43]
	v_mfma_f32_16x16x32_bf16 v[24:27], v[150:153], v[204:207], v[24:27]
	v_mfma_f32_16x16x32_bf16 v[16:19], v[162:165], v[204:207], v[16:19]
	v_mfma_f32_16x16x32_bf16 v[0:3], v[162:165], v[212:215], v[0:3]
	v_mfma_f32_16x16x32_bf16 v[8:11], v[150:153], v[212:215], v[8:11]
	v_mfma_f32_16x16x32_bf16 v[64:67], v[166:169], v[184:187], v[64:67]
	v_mfma_f32_16x16x32_bf16 v[52:55], v[174:177], v[184:187], v[52:55]
	v_mfma_f32_16x16x32_bf16 v[36:39], v[174:177], v[192:195], v[36:39]
	v_mfma_f32_16x16x32_bf16 v[44:47], v[166:169], v[192:195], v[44:47]
	v_mfma_f32_16x16x32_bf16 v[28:31], v[166:169], v[200:203], v[28:31]
	v_mfma_f32_16x16x32_bf16 v[20:23], v[174:177], v[200:203], v[20:23]
	v_mfma_f32_16x16x32_bf16 v[4:7], v[174:177], v[208:211], v[4:7]
	v_mfma_f32_16x16x32_bf16 v[12:15], v[166:169], v[208:211], v[12:15]
	v_mfma_f32_16x16x32_bf16 v[64:67], v[170:173], v[188:191], v[64:67]
	v_mfma_f32_16x16x32_bf16 v[52:55], v[180:183], v[188:191], v[52:55]
	v_mfma_f32_16x16x32_bf16 v[36:39], v[180:183], v[196:199], v[36:39]
	v_mfma_f32_16x16x32_bf16 v[44:47], v[170:173], v[196:199], v[44:47]
	v_mfma_f32_16x16x32_bf16 v[28:31], v[170:173], v[204:207], v[28:31]
	v_mfma_f32_16x16x32_bf16 v[20:23], v[180:183], v[204:207], v[20:23]
	v_mfma_f32_16x16x32_bf16 v[4:7], v[180:183], v[212:215], v[4:7]
	v_mfma_f32_16x16x32_bf16 v[12:15], v[170:173], v[212:215], v[12:15]
	s_barrier
; #define PG8_BAR __builtin_amdgcn_s_barrier()
; template <class Epi, class Sched, bool ALIGN_EPI = false, bool SP2 = false>
; __device__ __forceinline__ void gemm_phase(PG8_LAS unsigned char* lds, const Gemm g, const Sched& S, const Epi& E) {
;     ...
;         for (int t = (Epi::PEEL ? 2 : 0); t < nt; t += 2) {
;             const bool last = (t == nt - 2);
;             const char* a1 = cA + (size_t)(t + 1) * kstepA;
;             const char* a2 = last ? nA : cA + (size_t)(t + 2) * kstepA; const char* b2 = last ? nB : cB + (size_t)(t + 2) * kstepB;
;             const char* a3 = a2 + kstepA; const char* b3 = b2 + kstepB;
;             PG8_ITER(8);
;         }
;     ...
;         if constexpr (ALIGN_EPI) { if (wr == 0) PG8_BAR; }
	s_setprio 1
	ds_read_b128 v[146:149], v144
	ds_read_b128 v[150:153], v144 offset:1024
	ds_read_b128 v[158:161], v144 offset:2048
	ds_read_b128 v[162:165], v144 offset:3072
	ds_read_b128 v[166:169], v145
	ds_read_b128 v[170:173], v145 offset:1024
	ds_read_b128 v[174:177], v145 offset:2048
	ds_read_b128 v[180:183], v145 offset:3072
	s_add_u32 s10, s44, 0x4000
	s_addc_u32 s11, s45, 0
	s_mov_b32 m0, s46
	ds_read_b128 v[184:187], v156 offset:32768
	ds_read_b128 v[188:191], v156 offset:33792
	ds_read_b128 v[192:195], v156 offset:34816
	ds_read_b128 v[196:199], v156 offset:35840
	ds_read_b128 v[200:203], v156 offset:36864
	ds_read_b128 v[204:207], v156 offset:37888
	ds_read_b128 v[208:211], v156 offset:38912
	ds_read_b128 v[212:215], v156 offset:39936
	global_load_lds_dwordx4 v130, s[10:11]
	s_mov_b32 m0, s47
	s_nop 0
	global_load_lds_dwordx4 v134, s[10:11]
	s_setprio 0
	s_waitcnt vmcnt(8)
	s_waitcnt lgkmcnt(0)
	s_barrier
	s_waitcnt lgkmcnt(0)
	v_mfma_f32_16x16x32_bf16 v[122:125], v[146:149], v[184:187], v[122:125]
	v_mfma_f32_16x16x32_bf16 v[114:117], v[158:161], v[184:187], v[114:117]
	v_mfma_f32_16x16x32_bf16 v[98:101], v[158:161], v[192:195], v[98:101]
	v_mfma_f32_16x16x32_bf16 v[106:109], v[146:149], v[192:195], v[106:109]
	v_mfma_f32_16x16x32_bf16 v[88:91], v[146:149], v[200:203], v[88:91]
	v_mfma_f32_16x16x32_bf16 v[80:83], v[158:161], v[200:203], v[80:83]
	v_mfma_f32_16x16x32_bf16 v[60:63], v[158:161], v[208:211], v[60:63]
	v_mfma_f32_16x16x32_bf16 v[72:75], v[146:149], v[208:211], v[72:75]
	v_mfma_f32_16x16x32_bf16 v[122:125], v[150:153], v[188:191], v[122:125]
	v_mfma_f32_16x16x32_bf16 v[114:117], v[162:165], v[188:191], v[114:117]
	v_mfma_f32_16x16x32_bf16 v[98:101], v[162:165], v[196:199], v[98:101]
	v_mfma_f32_16x16x32_bf16 v[106:109], v[150:153], v[196:199], v[106:109]
	v_mfma_f32_16x16x32_bf16 v[88:91], v[150:153], v[204:207], v[88:91]
	v_mfma_f32_16x16x32_bf16 v[80:83], v[162:165], v[204:207], v[80:83]
	v_mfma_f32_16x16x32_bf16 v[60:63], v[162:165], v[212:215], v[60:63]
	v_mfma_f32_16x16x32_bf16 v[72:75], v[150:153], v[212:215], v[72:75]
	v_mfma_f32_16x16x32_bf16 v[126:129], v[166:169], v[184:187], v[126:129]
	v_mfma_f32_16x16x32_bf16 v[118:121], v[174:177], v[184:187], v[118:121]
	v_mfma_f32_16x16x32_bf16 v[102:105], v[174:177], v[192:195], v[102:105]
	v_mfma_f32_16x16x32_bf16 v[110:113], v[166:169], v[192:195], v[110:113]
	v_mfma_f32_16x16x32_bf16 v[92:95], v[166:169], v[200:203], v[92:95]
	v_mfma_f32_16x16x32_bf16 v[84:87], v[174:177], v[200:203], v[84:87]
	v_mfma_f32_16x16x32_bf16 v[68:71], v[174:177], v[208:211], v[68:71]
	v_mfma_f32_16x16x32_bf16 v[76:79], v[166:169], v[208:211], v[76:79]
	v_mfma_f32_16x16x32_bf16 v[126:129], v[170:173], v[188:191], v[126:129]
	v_mfma_f32_16x16x32_bf16 v[118:121], v[180:183], v[188:191], v[118:121]
	v_mfma_f32_16x16x32_bf16 v[102:105], v[180:183], v[196:199], v[102:105]
	v_mfma_f32_16x16x32_bf16 v[110:113], v[170:173], v[196:199], v[110:113]
	v_mfma_f32_16x16x32_bf16 v[92:95], v[170:173], v[204:207], v[92:95]
	v_mfma_f32_16x16x32_bf16 v[84:87], v[180:183], v[204:207], v[84:87]
	v_mfma_f32_16x16x32_bf16 v[68:71], v[180:183], v[212:215], v[68:71]
	v_mfma_f32_16x16x32_bf16 v[76:79], v[170:173], v[212:215], v[76:79]
	s_barrier
	s_setprio 1
	s_mov_b32 m0, s99
	s_add_u32 s100, s42, 0x80
	s_addc_u32 s101, s43, 0
	s_add_u32 s10, s42, 0x40080
	ds_read_b128 v[184:187], v156 offset:49152
	ds_read_b128 v[188:191], v156 offset:50176
	ds_read_b128 v[192:195], v156 offset:51200
	ds_read_b128 v[196:199], v156 offset:52224
	ds_read_b128 v[200:203], v156 offset:53248
	ds_read_b128 v[204:207], v156 offset:54272
	ds_read_b128 v[208:211], v156 offset:55296
	ds_read_b128 v[212:215], v156 offset:56320
	global_load_lds_dwordx4 v132, s[100:101]
	s_mov_b32 m0, vcc_lo
	s_addc_u32 s11, s43, 0
	global_load_lds_dwordx4 v136, s[100:101]
	s_mov_b32 m0, vcc_hi
	s_nop 0
	global_load_lds_dwordx4 v132, s[10:11]
	s_mov_b32 m0, s38
	s_nop 0
	global_load_lds_dwordx4 v136, s[10:11]
	s_mov_b32 m0, s49
	s_nop 0
	global_load_lds_dwordx4 v130, s[34:35]
	s_mov_b32 m0, s50
	s_nop 0
	global_load_lds_dwordx4 v134, s[34:35]
	s_setprio 0
	s_waitcnt vmcnt(8)
	s_waitcnt lgkmcnt(0)
	s_barrier
	s_waitcnt lgkmcnt(0)
	v_mfma_f32_16x16x32_bf16 v[56:59], v[146:149], v[184:187], v[56:59]
	v_mfma_f32_16x16x32_bf16 v[48:51], v[158:161], v[184:187], v[48:51]
	v_mfma_f32_16x16x32_bf16 v[32:35], v[158:161], v[192:195], v[32:35]
	v_mfma_f32_16x16x32_bf16 v[40:43], v[146:149], v[192:195], v[40:43]
	v_mfma_f32_16x16x32_bf16 v[24:27], v[146:149], v[200:203], v[24:27]
	v_mfma_f32_16x16x32_bf16 v[16:19], v[158:161], v[200:203], v[16:19]
	v_mfma_f32_16x16x32_bf16 v[0:3], v[158:161], v[208:211], v[0:3]
	v_mfma_f32_16x16x32_bf16 v[8:11], v[146:149], v[208:211], v[8:11]
	v_mfma_f32_16x16x32_bf16 v[56:59], v[150:153], v[188:191], v[56:59]
	v_mfma_f32_16x16x32_bf16 v[48:51], v[162:165], v[188:191], v[48:51]
	v_mfma_f32_16x16x32_bf16 v[32:35], v[162:165], v[196:199], v[32:35]
	v_mfma_f32_16x16x32_bf16 v[40:43], v[150:153], v[196:199], v[40:43]
	v_mfma_f32_16x16x32_bf16 v[24:27], v[150:153], v[204:207], v[24:27]
	v_mfma_f32_16x16x32_bf16 v[16:19], v[162:165], v[204:207], v[16:19]
	v_mfma_f32_16x16x32_bf16 v[0:3], v[162:165], v[212:215], v[0:3]
	v_mfma_f32_16x16x32_bf16 v[8:11], v[150:153], v[212:215], v[8:11]
	v_mfma_f32_16x16x32_bf16 v[64:67], v[166:169], v[184:187], v[64:67]
	v_mfma_f32_16x16x32_bf16 v[52:55], v[174:177], v[184:187], v[52:55]
	v_mfma_f32_16x16x32_bf16 v[36:39], v[174:177], v[192:195], v[36:39]
	v_mfma_f32_16x16x32_bf16 v[44:47], v[166:169], v[192:195], v[44:47]
	v_mfma_f32_16x16x32_bf16 v[28:31], v[166:169], v[200:203], v[28:31]
	v_mfma_f32_16x16x32_bf16 v[20:23], v[174:177], v[200:203], v[20:23]
	v_mfma_f32_16x16x32_bf16 v[4:7], v[174:177], v[208:211], v[4:7]
	v_mfma_f32_16x16x32_bf16 v[12:15], v[166:169], v[208:211], v[12:15]
	v_mfma_f32_16x16x32_bf16 v[64:67], v[170:173], v[188:191], v[64:67]
	v_mfma_f32_16x16x32_bf16 v[52:55], v[180:183], v[188:191], v[52:55]
	v_mfma_f32_16x16x32_bf16 v[36:39], v[180:183], v[196:199], v[36:39]
	v_mfma_f32_16x16x32_bf16 v[44:47], v[170:173], v[196:199], v[44:47]
	v_mfma_f32_16x16x32_bf16 v[28:31], v[170:173], v[204:207], v[28:31]
	v_mfma_f32_16x16x32_bf16 v[20:23], v[180:183], v[204:207], v[20:23]
	v_mfma_f32_16x16x32_bf16 v[4:7], v[180:183], v[212:215], v[4:7]
	v_mfma_f32_16x16x32_bf16 v[12:15], v[170:173], v[212:215], v[12:15]
	s_barrier
	s_setprio 1
	s_add_i32 s18, s18, 2
	s_add_u32 s3, s3, 0x100
	s_addc_u32 s2, s2, 0
	s_add_u32 s0, s0, 0x800000
	s_addc_u32 s1, s1, 0
	s_cmp_gt_u32 s18, 13
	s_cbranch_scc0 .LBB0_478
	s_and_b64 vcc, exec, s[16:17]
	s_cbranch_vccz .LBB0_481
	s_barrier

; #define PG8_WAIT_V(n) asm volatile("s_waitcnt vmcnt(" #n ")" ::: "memory")
; #define PG8_BAR __builtin_amdgcn_s_barrier()
; template <class Epi, class Sched, bool ALIGN_EPI = false, bool SP2 = false>
; __device__ __forceinline__ void gemm_phase(PG8_LAS unsigned char* lds, const Gemm g, const Sched& S, const Epi& E) {
;     ...
;     PG8_WAIT_V(0);
;     if constexpr (!ALIGN_EPI) { if (wr == 0) PG8_BAR; }
;     PG8_BAR;
.LBB0_518:
	s_setprio 0
	s_waitcnt vmcnt(0)
	v_readlane_b32 s52, v254, 58
	v_readlane_b32 s38, v255, 19
	v_readlane_b32 s50, v254, 56
	v_readlane_b32 s53, v254, 59
	v_readlane_b32 s56, v254, 60
	v_readlane_b32 s39, v255, 20
	v_readlane_b32 s19, v254, 48
	v_readlane_b32 s22, v254, 49
	v_readlane_b32 s23, v254, 50
	v_readlane_b32 s44, v254, 51
	v_readlane_b32 s45, v254, 52
	v_readlane_b32 s46, v254, 53
	v_readlane_b32 s47, v254, 54
	v_readlane_b32 s48, v254, 55
	v_readlane_b32 s51, v254, 57
	v_readlane_b32 s57, v254, 61
	v_readlane_b32 s49, v254, 62
	s_mov_b32 s53, 0x409b43d5
	v_readlane_b32 s31, v255, 17
	s_barrier
